# v024 + MFMA segments of all GEMM K-loops: redundant lgkmcnt(0) after the barrier and the mid-segment setprio 0/1 pair removed
# speedup vs baseline: 1.0099x; 1.0040x over previous
.LBB0_468:
	s_add_u32 s10, s6, 0xfffc0080
	s_addc_u32 s11, s7, -1
	s_add_i32 s52, 0, 0x10000
	s_cmp_eq_u32 s35, 12
	s_cselect_b32 s15, s9, s11
	s_cselect_b32 s14, s13, s10
	s_cselect_b32 s11, s16, s34
	s_cselect_b32 s10, s17, s33
	s_add_i32 s55, 0, 0x14000
	v_add_u32_e32 v14, s52, v209
	v_add_u32_e32 v30, s55, v209
	ds_read_b128 v[2:5], v14
	ds_read_b128 v[6:9], v14 offset:1024
	ds_read_b128 v[10:13], v14 offset:2048
	ds_read_b128 v[14:17], v14 offset:3072
	ds_read_b128 v[18:21], v30
	ds_read_b128 v[22:25], v30 offset:1024
	ds_read_b128 v[26:29], v30 offset:2048
	ds_read_b128 v[30:33], v30 offset:3072
	v_lshl_add_u64 v[216:217], s[6:7], 0, v[186:187]
	s_add_i32 m0, s44, 0xc000
	ds_read_b128 v[66:69], v215
	ds_read_b128 v[70:73], v215 offset:1024
	ds_read_b128 v[82:85], v215 offset:2048
	ds_read_b128 v[86:89], v215 offset:3072
	ds_read_b128 v[190:193], v215 offset:4096
	ds_read_b128 v[194:197], v215 offset:5120
	ds_read_b128 v[198:201], v215 offset:6144
	ds_read_b128 v[202:205], v215 offset:7168
	global_load_lds_dwordx4 v[216:217], off
	v_lshl_add_u64 v[216:217], s[6:7], 0, v[188:189]
	s_add_i32 m0, s44, 0xe000
	s_nop 0
	global_load_lds_dwordx4 v[216:217], off
	s_waitcnt vmcnt(8)
	s_waitcnt lgkmcnt(0)
	s_barrier
	s_setprio 1
	v_mfma_f32_16x16x32_bf16 v[174:177], v[2:5], v[66:69], v[174:177]
	v_mfma_f32_16x16x32_bf16 v[170:173], v[10:13], v[66:69], v[170:173]
	v_mfma_f32_16x16x32_bf16 v[158:161], v[2:5], v[82:85], v[158:161]
	v_mfma_f32_16x16x32_bf16 v[154:157], v[10:13], v[82:85], v[154:157]
	v_mfma_f32_16x16x32_bf16 v[142:145], v[2:5], v[190:193], v[142:145]
	v_mfma_f32_16x16x32_bf16 v[138:141], v[10:13], v[190:193], v[138:141]
	v_mfma_f32_16x16x32_bf16 v[126:129], v[2:5], v[198:201], v[126:129]
	v_mfma_f32_16x16x32_bf16 v[122:125], v[10:13], v[198:201], v[122:125]
	v_mfma_f32_16x16x32_bf16 v[174:177], v[6:9], v[70:73], v[174:177]
	v_mfma_f32_16x16x32_bf16 v[170:173], v[14:17], v[70:73], v[170:173]
	v_mfma_f32_16x16x32_bf16 v[158:161], v[6:9], v[86:89], v[158:161]
	v_mfma_f32_16x16x32_bf16 v[154:157], v[14:17], v[86:89], v[154:157]
	v_mfma_f32_16x16x32_bf16 v[142:145], v[6:9], v[194:197], v[142:145]
	v_mfma_f32_16x16x32_bf16 v[138:141], v[14:17], v[194:197], v[138:141]
	v_mfma_f32_16x16x32_bf16 v[126:129], v[6:9], v[202:205], v[126:129]
	v_mfma_f32_16x16x32_bf16 v[122:125], v[14:17], v[202:205], v[122:125]
	v_mfma_f32_16x16x32_bf16 v[166:169], v[18:21], v[66:69], v[166:169]
	v_mfma_f32_16x16x32_bf16 v[66:69], v[26:29], v[66:69], v[162:165]
	v_mfma_f32_16x16x32_bf16 v[166:169], v[22:25], v[70:73], v[166:169]
	v_mfma_f32_16x16x32_bf16 v[66:69], v[30:33], v[70:73], v[66:69]
	v_mfma_f32_16x16x32_bf16 v[70:73], v[18:21], v[82:85], v[150:153]
	v_mfma_f32_16x16x32_bf16 v[82:85], v[26:29], v[82:85], v[146:149]
	v_mfma_f32_16x16x32_bf16 v[130:133], v[26:29], v[190:193], v[130:133]
	v_mfma_f32_16x16x32_bf16 v[118:121], v[18:21], v[198:201], v[118:121]
	v_mfma_f32_16x16x32_bf16 v[114:117], v[26:29], v[198:201], v[114:117]
	v_mfma_f32_16x16x32_bf16 v[70:73], v[22:25], v[86:89], v[70:73]
	v_mfma_f32_16x16x32_bf16 v[82:85], v[30:33], v[86:89], v[82:85]
	v_mfma_f32_16x16x32_bf16 v[86:89], v[18:21], v[190:193], v[134:137]
	v_mfma_f32_16x16x32_bf16 v[130:133], v[30:33], v[194:197], v[130:133]
	v_mfma_f32_16x16x32_bf16 v[118:121], v[22:25], v[202:205], v[118:121]
	v_mfma_f32_16x16x32_bf16 v[114:117], v[30:33], v[202:205], v[114:117]
	v_mfma_f32_16x16x32_bf16 v[86:89], v[22:25], v[194:197], v[86:89]
	s_setprio 0
	s_barrier
	s_add_i32 s52, s52, s63
	v_lshl_add_u64 v[232:233], s[10:11], 0, v[0:1]
	s_mov_b32 m0, s52
	ds_read_b128 v[134:137], v215 offset:16384
	ds_read_b128 v[146:149], v215 offset:17408
	ds_read_b128 v[150:153], v215 offset:18432
	ds_read_b128 v[162:165], v215 offset:19456
	ds_read_b128 v[190:193], v215 offset:20480
	ds_read_b128 v[194:197], v215 offset:21504
	ds_read_b128 v[198:201], v215 offset:22528
	ds_read_b128 v[202:205], v215 offset:23552
	global_load_lds_dwordx4 v[232:233], off
	s_add_i32 m0, s52, 0x2000
	s_add_u32 s52, s10, 0x40000
	v_lshl_add_u64 v[234:235], s[10:11], 0, v[182:183]
	s_addc_u32 s53, s11, 0
	s_add_i32 s55, s55, s63
	global_load_lds_dwordx4 v[234:235], off
	v_lshl_add_u64 v[216:217], s[52:53], 0, v[0:1]
	s_mov_b32 m0, s55
	v_lshl_add_u64 v[236:237], s[14:15], 0, v[178:179]
	global_load_lds_dwordx4 v[216:217], off
	v_lshl_add_u64 v[216:217], s[52:53], 0, v[182:183]
	s_add_i32 m0, s55, 0x2000
	v_lshl_add_u64 v[238:239], s[14:15], 0, v[180:181]
	global_load_lds_dwordx4 v[216:217], off
	s_mov_b32 m0, s44
	s_nop 0
	global_load_lds_dwordx4 v[236:237], off
	s_mov_b32 m0, s45
	s_nop 0
	global_load_lds_dwordx4 v[238:239], off
	s_waitcnt vmcnt(8)
	s_waitcnt lgkmcnt(0)
	s_barrier
	s_setprio 1
	v_mfma_f32_16x16x32_bf16 v[110:113], v[2:5], v[134:137], v[110:113]
	v_mfma_f32_16x16x32_bf16 v[106:109], v[10:13], v[134:137], v[106:109]
	v_mfma_f32_16x16x32_bf16 v[94:97], v[2:5], v[150:153], v[94:97]
	v_mfma_f32_16x16x32_bf16 v[90:93], v[10:13], v[150:153], v[90:93]
	v_mfma_f32_16x16x32_bf16 v[62:65], v[2:5], v[190:193], v[62:65]
	v_mfma_f32_16x16x32_bf16 v[58:61], v[10:13], v[190:193], v[58:61]
	v_mfma_f32_16x16x32_bf16 v[2:5], v[2:5], v[198:201], v[46:49]
	v_mfma_f32_16x16x32_bf16 v[110:113], v[6:9], v[146:149], v[110:113]
	v_mfma_f32_16x16x32_bf16 v[106:109], v[14:17], v[146:149], v[106:109]
	v_mfma_f32_16x16x32_bf16 v[94:97], v[6:9], v[162:165], v[94:97]
	v_mfma_f32_16x16x32_bf16 v[90:93], v[14:17], v[162:165], v[90:93]
	v_mfma_f32_16x16x32_bf16 v[62:65], v[6:9], v[194:197], v[62:65]
	v_mfma_f32_16x16x32_bf16 v[58:61], v[14:17], v[194:197], v[58:61]
	v_mfma_f32_16x16x32_bf16 v[2:5], v[6:9], v[202:205], v[2:5]
	v_mfma_f32_16x16x32_bf16 v[6:9], v[10:13], v[198:201], v[42:45]
	v_mfma_f32_16x16x32_bf16 v[6:9], v[14:17], v[202:205], v[6:9]
	v_mfma_f32_16x16x32_bf16 v[42:45], v[18:21], v[150:153], v[78:81]
	v_mfma_f32_16x16x32_bf16 v[78:81], v[22:25], v[162:165], v[42:45]
	v_mfma_f32_16x16x32_bf16 v[42:45], v[26:29], v[150:153], v[74:77]
	v_mfma_f32_16x16x32_bf16 v[74:77], v[30:33], v[162:165], v[42:45]
	v_mfma_f32_16x16x32_bf16 v[42:45], v[18:21], v[190:193], v[54:57]
	v_mfma_f32_16x16x32_bf16 v[10:13], v[18:21], v[134:137], v[102:105]
	v_mfma_f32_16x16x32_bf16 v[54:57], v[22:25], v[194:197], v[42:45]
	v_mfma_f32_16x16x32_bf16 v[42:45], v[26:29], v[190:193], v[50:53]
	v_mfma_f32_16x16x32_bf16 v[18:21], v[18:21], v[198:201], v[38:41]
	v_mfma_f32_16x16x32_bf16 v[10:13], v[22:25], v[146:149], v[10:13]
	v_mfma_f32_16x16x32_bf16 v[14:17], v[26:29], v[134:137], v[98:101]
	v_mfma_f32_16x16x32_bf16 v[50:53], v[30:33], v[194:197], v[42:45]
	v_mfma_f32_16x16x32_bf16 v[18:21], v[22:25], v[202:205], v[18:21]
	v_mfma_f32_16x16x32_bf16 v[22:25], v[26:29], v[198:201], v[34:37]
	v_mfma_f32_16x16x32_bf16 v[14:17], v[30:33], v[146:149], v[14:17]
	v_mfma_f32_16x16x32_bf16 v[22:25], v[30:33], v[202:205], v[22:25]
	s_setprio 0
	s_barrier
	s_add_i32 s52, 0, 0x18000
	s_add_i32 s53, 0, 0x1c000
	v_add_u32_e32 v38, s52, v209
	v_add_u32_e32 v42, s53, v209
	ds_read_b128 v[26:29], v38
	ds_read_b128 v[30:33], v38 offset:1024
	ds_read_b128 v[34:37], v38 offset:2048
	ds_read_b128 v[38:41], v38 offset:3072
	ds_read_b128 v[190:193], v42
	ds_read_b128 v[194:197], v42 offset:1024
	ds_read_b128 v[198:201], v42 offset:2048
	ds_read_b128 v[202:205], v42 offset:3072
	s_add_u32 s14, s14, 0x40000
	s_addc_u32 s15, s15, 0
	s_mov_b32 m0, s48
	v_lshl_add_u64 v[134:135], s[14:15], 0, v[178:179]
	ds_read_b128 v[42:45], v215 offset:32768
	ds_read_b128 v[46:49], v215 offset:33792
	ds_read_b128 v[98:101], v215 offset:34816
	ds_read_b128 v[102:105], v215 offset:35840
	ds_read_b128 v[216:219], v215 offset:36864
	ds_read_b128 v[220:223], v215 offset:37888
	ds_read_b128 v[224:227], v215 offset:38912
	ds_read_b128 v[228:231], v215 offset:39936
	global_load_lds_dwordx4 v[134:135], off
	v_lshl_add_u64 v[134:135], s[14:15], 0, v[180:181]
	s_mov_b32 m0, s49
	s_nop 0
	global_load_lds_dwordx4 v[134:135], off
	s_waitcnt vmcnt(8)
	s_waitcnt lgkmcnt(0)
	s_barrier
	s_setprio 1
	v_mfma_f32_16x16x32_bf16 v[134:137], v[26:29], v[42:45], v[174:177]
	v_mfma_f32_16x16x32_bf16 v[174:177], v[30:33], v[46:49], v[134:137]
	v_mfma_f32_16x16x32_bf16 v[134:137], v[34:37], v[42:45], v[170:173]
	v_mfma_f32_16x16x32_bf16 v[170:173], v[38:41], v[46:49], v[134:137]
	v_mfma_f32_16x16x32_bf16 v[134:137], v[26:29], v[98:101], v[158:161]
	v_mfma_f32_16x16x32_bf16 v[158:161], v[30:33], v[102:105], v[134:137]
	v_mfma_f32_16x16x32_bf16 v[134:137], v[34:37], v[98:101], v[154:157]
	v_mfma_f32_16x16x32_bf16 v[154:157], v[38:41], v[102:105], v[134:137]
	v_mfma_f32_16x16x32_bf16 v[134:137], v[26:29], v[216:219], v[142:145]
	v_mfma_f32_16x16x32_bf16 v[142:145], v[30:33], v[220:223], v[134:137]
	v_mfma_f32_16x16x32_bf16 v[134:137], v[34:37], v[216:219], v[138:141]
	v_mfma_f32_16x16x32_bf16 v[126:129], v[26:29], v[224:227], v[126:129]
	v_mfma_f32_16x16x32_bf16 v[122:125], v[34:37], v[224:227], v[122:125]
	v_mfma_f32_16x16x32_bf16 v[138:141], v[38:41], v[220:223], v[134:137]
	v_mfma_f32_16x16x32_bf16 v[126:129], v[30:33], v[228:231], v[126:129]
	v_mfma_f32_16x16x32_bf16 v[122:125], v[38:41], v[228:231], v[122:125]
	v_mfma_f32_16x16x32_bf16 v[134:137], v[190:193], v[42:45], v[166:169]
	v_mfma_f32_16x16x32_bf16 v[42:45], v[198:201], v[42:45], v[66:69]
	v_mfma_f32_16x16x32_bf16 v[162:165], v[202:205], v[46:49], v[42:45]
	v_mfma_f32_16x16x32_bf16 v[42:45], v[190:193], v[98:101], v[70:73]
	v_mfma_f32_16x16x32_bf16 v[150:153], v[194:197], v[102:105], v[42:45]
	v_mfma_f32_16x16x32_bf16 v[42:45], v[198:201], v[98:101], v[82:85]
	v_mfma_f32_16x16x32_bf16 v[146:149], v[202:205], v[102:105], v[42:45]
	v_mfma_f32_16x16x32_bf16 v[42:45], v[190:193], v[216:219], v[86:89]
	v_mfma_f32_16x16x32_bf16 v[166:169], v[194:197], v[46:49], v[134:137]
	v_mfma_f32_16x16x32_bf16 v[134:137], v[194:197], v[220:223], v[42:45]
	v_mfma_f32_16x16x32_bf16 v[42:45], v[198:201], v[216:219], v[130:133]
	v_mfma_f32_16x16x32_bf16 v[130:133], v[202:205], v[220:223], v[42:45]
	v_mfma_f32_16x16x32_bf16 v[42:45], v[190:193], v[224:227], v[118:121]
	v_mfma_f32_16x16x32_bf16 v[118:121], v[194:197], v[228:231], v[42:45]
	v_mfma_f32_16x16x32_bf16 v[42:45], v[198:201], v[224:227], v[114:117]
	v_mfma_f32_16x16x32_bf16 v[114:117], v[202:205], v[228:231], v[42:45]
	s_setprio 0
	s_barrier
	s_add_i32 s14, s52, s63
	s_nop 3
	v_lshl_add_u64 v[42:43], v[232:233], 0, s[80:81]
	s_mov_b32 m0, s14
	ds_read_b128 v[66:69], v215 offset:49152
	ds_read_b128 v[70:73], v215 offset:50176
	ds_read_b128 v[82:85], v215 offset:51200
	ds_read_b128 v[86:89], v215 offset:52224
	ds_read_b128 v[216:219], v215 offset:53248
	ds_read_b128 v[220:223], v215 offset:54272
	ds_read_b128 v[224:227], v215 offset:55296
	ds_read_b128 v[228:231], v215 offset:56320
	global_load_lds_dwordx4 v[42:43], off
	s_add_i32 m0, s14, 0x2000
	s_add_u32 s10, s10, 0x40080
	v_lshl_add_u64 v[42:43], v[234:235], 0, s[80:81]
	s_addc_u32 s11, s11, 0
	s_add_i32 s14, s53, s63
	global_load_lds_dwordx4 v[42:43], off
	v_lshl_add_u64 v[42:43], s[10:11], 0, v[0:1]
	s_mov_b32 m0, s14
	s_nop 0
	global_load_lds_dwordx4 v[42:43], off
	v_lshl_add_u64 v[42:43], s[10:11], 0, v[182:183]
	s_add_i32 m0, s14, 0x2000
	s_nop 0
	global_load_lds_dwordx4 v[42:43], off
	v_lshl_add_u64 v[42:43], v[236:237], 0, s[80:81]
	s_mov_b32 m0, s1
	s_nop 0
	global_load_lds_dwordx4 v[42:43], off
	v_lshl_add_u64 v[42:43], v[238:239], 0, s[80:81]
	s_mov_b32 m0, s0
	s_nop 0
	global_load_lds_dwordx4 v[42:43], off
	s_waitcnt vmcnt(8)
	s_waitcnt lgkmcnt(0)
	s_barrier
	s_setprio 1
	v_mfma_f32_16x16x32_bf16 v[42:45], v[26:29], v[66:69], v[110:113]
	v_mfma_f32_16x16x32_bf16 v[110:113], v[30:33], v[70:73], v[42:45]
	v_mfma_f32_16x16x32_bf16 v[42:45], v[34:37], v[66:69], v[106:109]
	v_mfma_f32_16x16x32_bf16 v[106:109], v[38:41], v[70:73], v[42:45]
	v_mfma_f32_16x16x32_bf16 v[42:45], v[26:29], v[82:85], v[94:97]
	v_mfma_f32_16x16x32_bf16 v[94:97], v[30:33], v[86:89], v[42:45]
	v_mfma_f32_16x16x32_bf16 v[42:45], v[34:37], v[82:85], v[90:93]
	v_mfma_f32_16x16x32_bf16 v[90:93], v[38:41], v[86:89], v[42:45]
	v_mfma_f32_16x16x32_bf16 v[42:45], v[26:29], v[216:219], v[62:65]
	v_mfma_f32_16x16x32_bf16 v[2:5], v[26:29], v[224:227], v[2:5]
	v_mfma_f32_16x16x32_bf16 v[62:65], v[30:33], v[220:223], v[42:45]
	v_mfma_f32_16x16x32_bf16 v[42:45], v[34:37], v[216:219], v[58:61]
	v_mfma_f32_16x16x32_bf16 v[46:49], v[30:33], v[228:231], v[2:5]
	v_mfma_f32_16x16x32_bf16 v[2:5], v[34:37], v[224:227], v[6:9]
	v_mfma_f32_16x16x32_bf16 v[58:61], v[38:41], v[220:223], v[42:45]
	v_mfma_f32_16x16x32_bf16 v[42:45], v[38:41], v[228:231], v[2:5]
	v_mfma_f32_16x16x32_bf16 v[2:5], v[190:193], v[66:69], v[10:13]
	v_mfma_f32_16x16x32_bf16 v[102:105], v[194:197], v[70:73], v[2:5]
	v_mfma_f32_16x16x32_bf16 v[2:5], v[198:201], v[66:69], v[14:17]
	v_mfma_f32_16x16x32_bf16 v[98:101], v[202:205], v[70:73], v[2:5]
	v_mfma_f32_16x16x32_bf16 v[2:5], v[190:193], v[82:85], v[78:81]
	v_mfma_f32_16x16x32_bf16 v[78:81], v[194:197], v[86:89], v[2:5]
	v_mfma_f32_16x16x32_bf16 v[2:5], v[198:201], v[82:85], v[74:77]
	v_mfma_f32_16x16x32_bf16 v[74:77], v[202:205], v[86:89], v[2:5]
	v_mfma_f32_16x16x32_bf16 v[2:5], v[190:193], v[216:219], v[54:57]
	v_mfma_f32_16x16x32_bf16 v[54:57], v[194:197], v[220:223], v[2:5]
	v_mfma_f32_16x16x32_bf16 v[2:5], v[198:201], v[216:219], v[50:53]
	v_mfma_f32_16x16x32_bf16 v[50:53], v[202:205], v[220:223], v[2:5]
	v_mfma_f32_16x16x32_bf16 v[2:5], v[190:193], v[224:227], v[18:21]
	v_mfma_f32_16x16x32_bf16 v[38:41], v[194:197], v[228:231], v[2:5]
	v_mfma_f32_16x16x32_bf16 v[2:5], v[198:201], v[224:227], v[22:25]
	v_mfma_f32_16x16x32_bf16 v[34:37], v[202:205], v[228:231], v[2:5]
	s_setprio 0
	s_barrier
	s_add_i32 s35, s35, 2
	s_add_u32 s6, s6, 0x100
	s_addc_u32 s7, s7, 0
	s_add_u32 s33, s33, 0x100
	s_addc_u32 s34, s34, 0
	s_cmp_gt_u32 s35, 13
	s_cbranch_scc0 .LBB0_468
	s_and_b64 vcc, exec, s[96:97]
	s_cbranch_vccz .LBB0_471
	s_barrier

.LBB0_1096:
	s_add_u32 s36, s4, 0xfffc0080
	s_addc_u32 s46, s5, -1
	s_add_i32 s50, 0, 0x10000
	s_cmp_eq_u32 s35, 12
	s_cselect_b32 s49, s21, s46
	s_cselect_b32 s48, s29, s36
	s_cselect_b32 s47, s19, s34
	s_cselect_b32 s46, s31, s33
	s_add_i32 s36, 0, 0x14000
	v_add_u32_e32 v62, s50, v245
	v_add_u32_e32 v94, s36, v245
	ds_read_b128 v[50:53], v62
	ds_read_b128 v[54:57], v62 offset:1024
	ds_read_b128 v[58:61], v62 offset:2048
	ds_read_b128 v[62:65], v62 offset:3072
	ds_read_b128 v[70:73], v94
	ds_read_b128 v[74:77], v94 offset:1024
	ds_read_b128 v[90:93], v94 offset:2048
	ds_read_b128 v[94:97], v94 offset:3072
	v_lshl_add_u64 v[194:195], s[4:5], 0, v[216:217]
	s_add_i32 m0, s56, 0xc000
	ds_read_b128 v[162:165], v252
	ds_read_b128 v[166:169], v252 offset:1024
	ds_read_b128 v[170:173], v252 offset:2048
	ds_read_b128 v[174:177], v252 offset:3072
	ds_read_b128 v[178:181], v252 offset:4096
	ds_read_b128 v[182:185], v252 offset:5120
	ds_read_b128 v[186:189], v252 offset:6144
	ds_read_b128 v[190:193], v252 offset:7168
	global_load_lds_dwordx4 v[194:195], off
	v_lshl_add_u64 v[194:195], s[4:5], 0, v[218:219]
	s_add_i32 m0, s56, 0xe000
	s_nop 0
	global_load_lds_dwordx4 v[194:195], off
	s_waitcnt vmcnt(8)
	s_waitcnt lgkmcnt(0)
	s_barrier
	s_setprio 1
	v_mfma_f32_16x16x32_bf16 v[158:161], v[50:53], v[162:165], v[158:161]
	v_mfma_f32_16x16x32_bf16 v[154:157], v[58:61], v[162:165], v[154:157]
	v_mfma_f32_16x16x32_bf16 v[142:145], v[50:53], v[170:173], v[142:145]
	v_mfma_f32_16x16x32_bf16 v[138:141], v[58:61], v[170:173], v[138:141]
	v_mfma_f32_16x16x32_bf16 v[126:129], v[50:53], v[178:181], v[126:129]
	v_mfma_f32_16x16x32_bf16 v[122:125], v[58:61], v[178:181], v[122:125]
	v_mfma_f32_16x16x32_bf16 v[110:113], v[50:53], v[186:189], v[110:113]
	v_mfma_f32_16x16x32_bf16 v[106:109], v[58:61], v[186:189], v[106:109]
	v_mfma_f32_16x16x32_bf16 v[158:161], v[54:57], v[166:169], v[158:161]
	v_mfma_f32_16x16x32_bf16 v[154:157], v[62:65], v[166:169], v[154:157]
	v_mfma_f32_16x16x32_bf16 v[142:145], v[54:57], v[174:177], v[142:145]
	v_mfma_f32_16x16x32_bf16 v[138:141], v[62:65], v[174:177], v[138:141]
	v_mfma_f32_16x16x32_bf16 v[126:129], v[54:57], v[182:185], v[126:129]
	v_mfma_f32_16x16x32_bf16 v[122:125], v[62:65], v[182:185], v[122:125]
	v_mfma_f32_16x16x32_bf16 v[110:113], v[54:57], v[190:193], v[110:113]
	v_mfma_f32_16x16x32_bf16 v[106:109], v[62:65], v[190:193], v[106:109]
	v_mfma_f32_16x16x32_bf16 v[150:153], v[70:73], v[162:165], v[150:153]
	v_mfma_f32_16x16x32_bf16 v[146:149], v[90:93], v[162:165], v[146:149]
	v_mfma_f32_16x16x32_bf16 v[134:137], v[70:73], v[170:173], v[134:137]
	v_mfma_f32_16x16x32_bf16 v[130:133], v[90:93], v[170:173], v[130:133]
	v_mfma_f32_16x16x32_bf16 v[118:121], v[70:73], v[178:181], v[118:121]
	v_mfma_f32_16x16x32_bf16 v[114:117], v[90:93], v[178:181], v[114:117]
	v_mfma_f32_16x16x32_bf16 v[102:105], v[70:73], v[186:189], v[102:105]
	v_mfma_f32_16x16x32_bf16 v[98:101], v[90:93], v[186:189], v[98:101]
	v_mfma_f32_16x16x32_bf16 v[150:153], v[74:77], v[166:169], v[150:153]
	v_mfma_f32_16x16x32_bf16 v[146:149], v[94:97], v[166:169], v[146:149]
	v_mfma_f32_16x16x32_bf16 v[134:137], v[74:77], v[174:177], v[134:137]
	v_mfma_f32_16x16x32_bf16 v[130:133], v[94:97], v[174:177], v[130:133]
	v_mfma_f32_16x16x32_bf16 v[118:121], v[74:77], v[182:185], v[118:121]
	v_mfma_f32_16x16x32_bf16 v[114:117], v[94:97], v[182:185], v[114:117]
	v_mfma_f32_16x16x32_bf16 v[102:105], v[74:77], v[190:193], v[102:105]
	v_mfma_f32_16x16x32_bf16 v[98:101], v[94:97], v[190:193], v[98:101]
	s_setprio 0
	s_barrier
	s_add_i32 s50, s50, s1
	v_lshl_add_u64 v[198:199], s[46:47], 0, v[0:1]
	s_mov_b32 m0, s50
	ds_read_b128 v[162:165], v252 offset:16384
	ds_read_b128 v[166:169], v252 offset:17408
	ds_read_b128 v[170:173], v252 offset:18432
	ds_read_b128 v[174:177], v252 offset:19456
	ds_read_b128 v[178:181], v252 offset:20480
	ds_read_b128 v[182:185], v252 offset:21504
	ds_read_b128 v[186:189], v252 offset:22528
	ds_read_b128 v[190:193], v252 offset:23552
	global_load_lds_dwordx4 v[198:199], off
	s_add_i32 m0, s50, 0x2000
	s_add_u32 s50, s46, 0x40000
	v_lshl_add_u64 v[200:201], s[46:47], 0, v[214:215]
	s_addc_u32 s51, s47, 0
	s_add_i32 s36, s36, s1
	global_load_lds_dwordx4 v[200:201], off
	v_lshl_add_u64 v[194:195], s[50:51], 0, v[0:1]
	s_mov_b32 m0, s36
	v_lshl_add_u64 v[202:203], s[48:49], 0, v[210:211]
	global_load_lds_dwordx4 v[194:195], off
	v_lshl_add_u64 v[194:195], s[50:51], 0, v[214:215]
	s_add_i32 m0, s36, 0x2000
	v_lshl_add_u64 v[204:205], s[48:49], 0, v[212:213]
	global_load_lds_dwordx4 v[194:195], off
	s_mov_b32 m0, s56
	s_nop 0
	global_load_lds_dwordx4 v[202:203], off
	s_mov_b32 m0, s57
	s_nop 0
	global_load_lds_dwordx4 v[204:205], off
	s_waitcnt vmcnt(8)
	s_waitcnt lgkmcnt(0)
	s_barrier
	s_setprio 1
	v_mfma_f32_16x16x32_bf16 v[86:89], v[50:53], v[162:165], v[86:89]
	v_mfma_f32_16x16x32_bf16 v[82:85], v[58:61], v[162:165], v[82:85]
	v_mfma_f32_16x16x32_bf16 v[46:49], v[50:53], v[170:173], v[46:49]
	v_mfma_f32_16x16x32_bf16 v[42:45], v[58:61], v[170:173], v[42:45]
	v_mfma_f32_16x16x32_bf16 v[30:33], v[50:53], v[178:181], v[30:33]
	v_mfma_f32_16x16x32_bf16 v[26:29], v[58:61], v[178:181], v[26:29]
	v_mfma_f32_16x16x32_bf16 v[14:17], v[50:53], v[186:189], v[14:17]
	v_mfma_f32_16x16x32_bf16 v[10:13], v[58:61], v[186:189], v[10:13]
	v_mfma_f32_16x16x32_bf16 v[86:89], v[54:57], v[166:169], v[86:89]
	v_mfma_f32_16x16x32_bf16 v[82:85], v[62:65], v[166:169], v[82:85]
	v_mfma_f32_16x16x32_bf16 v[46:49], v[54:57], v[174:177], v[46:49]
	v_mfma_f32_16x16x32_bf16 v[42:45], v[62:65], v[174:177], v[42:45]
	v_mfma_f32_16x16x32_bf16 v[30:33], v[54:57], v[182:185], v[30:33]
	v_mfma_f32_16x16x32_bf16 v[26:29], v[62:65], v[182:185], v[26:29]
	v_mfma_f32_16x16x32_bf16 v[14:17], v[54:57], v[190:193], v[14:17]
	v_mfma_f32_16x16x32_bf16 v[10:13], v[62:65], v[190:193], v[10:13]
	v_mfma_f32_16x16x32_bf16 v[38:41], v[70:73], v[170:173], v[38:41]
	v_mfma_f32_16x16x32_bf16 v[34:37], v[90:93], v[170:173], v[34:37]
	v_mfma_f32_16x16x32_bf16 v[22:25], v[70:73], v[178:181], v[22:25]
	v_mfma_f32_16x16x32_bf16 v[18:21], v[90:93], v[178:181], v[18:21]
	v_mfma_f32_16x16x32_bf16 v[6:9], v[70:73], v[186:189], v[6:9]
	v_mfma_f32_16x16x32_bf16 v[2:5], v[90:93], v[186:189], v[2:5]
	v_mfma_f32_16x16x32_bf16 v[50:53], v[70:73], v[162:165], v[78:81]
	v_mfma_f32_16x16x32_bf16 v[54:57], v[90:93], v[162:165], v[66:69]
	v_mfma_f32_16x16x32_bf16 v[38:41], v[74:77], v[174:177], v[38:41]
	v_mfma_f32_16x16x32_bf16 v[34:37], v[94:97], v[174:177], v[34:37]
	v_mfma_f32_16x16x32_bf16 v[22:25], v[74:77], v[182:185], v[22:25]
	v_mfma_f32_16x16x32_bf16 v[18:21], v[94:97], v[182:185], v[18:21]
	v_mfma_f32_16x16x32_bf16 v[6:9], v[74:77], v[190:193], v[6:9]
	v_mfma_f32_16x16x32_bf16 v[2:5], v[94:97], v[190:193], v[2:5]
	v_mfma_f32_16x16x32_bf16 v[50:53], v[74:77], v[166:169], v[50:53]
	v_mfma_f32_16x16x32_bf16 v[54:57], v[94:97], v[166:169], v[54:57]
	s_setprio 0
	s_barrier
	s_add_i32 s36, 0, 0x18000
	s_add_i32 s50, 0, 0x1c000
	v_add_u32_e32 v70, s36, v245
	v_add_u32_e32 v78, s50, v245
	ds_read_b128 v[58:61], v70
	ds_read_b128 v[62:65], v70 offset:1024
	ds_read_b128 v[66:69], v70 offset:2048
	ds_read_b128 v[70:73], v70 offset:3072
	ds_read_b128 v[74:77], v78
	ds_read_b128 v[90:93], v78 offset:1024
	ds_read_b128 v[94:97], v78 offset:2048
	ds_read_b128 v[162:165], v78 offset:3072
	s_add_u32 s48, s48, 0x40000
	s_addc_u32 s49, s49, 0
	s_mov_b32 m0, s62
	v_lshl_add_u64 v[194:195], s[48:49], 0, v[210:211]
	ds_read_b128 v[78:81], v252 offset:32768
	ds_read_b128 v[166:169], v252 offset:33792
	ds_read_b128 v[170:173], v252 offset:34816
	ds_read_b128 v[174:177], v252 offset:35840
	ds_read_b128 v[178:181], v252 offset:36864
	ds_read_b128 v[182:185], v252 offset:37888
	ds_read_b128 v[186:189], v252 offset:38912
	ds_read_b128 v[190:193], v252 offset:39936
	global_load_lds_dwordx4 v[194:195], off
	v_lshl_add_u64 v[194:195], s[48:49], 0, v[212:213]
	s_mov_b32 m0, s63
	s_nop 0
	global_load_lds_dwordx4 v[194:195], off
	s_waitcnt vmcnt(8)
	s_waitcnt lgkmcnt(0)
	s_barrier
	s_setprio 1
	v_mfma_f32_16x16x32_bf16 v[158:161], v[58:61], v[78:81], v[158:161]
	v_mfma_f32_16x16x32_bf16 v[154:157], v[66:69], v[78:81], v[154:157]
	v_mfma_f32_16x16x32_bf16 v[142:145], v[58:61], v[170:173], v[142:145]
	v_mfma_f32_16x16x32_bf16 v[138:141], v[66:69], v[170:173], v[138:141]
	v_mfma_f32_16x16x32_bf16 v[126:129], v[58:61], v[178:181], v[126:129]
	v_mfma_f32_16x16x32_bf16 v[122:125], v[66:69], v[178:181], v[122:125]
	v_mfma_f32_16x16x32_bf16 v[110:113], v[58:61], v[186:189], v[110:113]
	v_mfma_f32_16x16x32_bf16 v[106:109], v[66:69], v[186:189], v[106:109]
	v_mfma_f32_16x16x32_bf16 v[158:161], v[62:65], v[166:169], v[158:161]
	v_mfma_f32_16x16x32_bf16 v[154:157], v[70:73], v[166:169], v[154:157]
	v_mfma_f32_16x16x32_bf16 v[142:145], v[62:65], v[174:177], v[142:145]
	v_mfma_f32_16x16x32_bf16 v[138:141], v[70:73], v[174:177], v[138:141]
	v_mfma_f32_16x16x32_bf16 v[126:129], v[62:65], v[182:185], v[126:129]
	v_mfma_f32_16x16x32_bf16 v[122:125], v[70:73], v[182:185], v[122:125]
	v_mfma_f32_16x16x32_bf16 v[110:113], v[62:65], v[190:193], v[110:113]
	v_mfma_f32_16x16x32_bf16 v[106:109], v[70:73], v[190:193], v[106:109]
	v_mfma_f32_16x16x32_bf16 v[150:153], v[74:77], v[78:81], v[150:153]
	v_mfma_f32_16x16x32_bf16 v[78:81], v[94:97], v[78:81], v[146:149]
	v_mfma_f32_16x16x32_bf16 v[146:149], v[162:165], v[166:169], v[78:81]
	v_mfma_f32_16x16x32_bf16 v[78:81], v[74:77], v[170:173], v[134:137]
	v_mfma_f32_16x16x32_bf16 v[134:137], v[90:93], v[174:177], v[78:81]
	v_mfma_f32_16x16x32_bf16 v[78:81], v[94:97], v[170:173], v[130:133]
	v_mfma_f32_16x16x32_bf16 v[130:133], v[162:165], v[174:177], v[78:81]
	v_mfma_f32_16x16x32_bf16 v[78:81], v[74:77], v[178:181], v[118:121]
	v_mfma_f32_16x16x32_bf16 v[118:121], v[90:93], v[182:185], v[78:81]
	v_mfma_f32_16x16x32_bf16 v[78:81], v[94:97], v[178:181], v[114:117]
	v_mfma_f32_16x16x32_bf16 v[114:117], v[162:165], v[182:185], v[78:81]
	v_mfma_f32_16x16x32_bf16 v[78:81], v[74:77], v[186:189], v[102:105]
	v_mfma_f32_16x16x32_bf16 v[102:105], v[90:93], v[190:193], v[78:81]
	v_mfma_f32_16x16x32_bf16 v[78:81], v[94:97], v[186:189], v[98:101]
	v_mfma_f32_16x16x32_bf16 v[150:153], v[90:93], v[166:169], v[150:153]
	v_mfma_f32_16x16x32_bf16 v[98:101], v[162:165], v[190:193], v[78:81]
	s_setprio 0
	s_barrier
	s_add_i32 s36, s36, s1
	s_nop 2
	v_lshl_add_u64 v[78:79], v[198:199], 0, s[80:81]
	s_mov_b32 m0, s36
	ds_read_b128 v[166:169], v252 offset:49152
	ds_read_b128 v[170:173], v252 offset:50176
	ds_read_b128 v[174:177], v252 offset:51200
	ds_read_b128 v[178:181], v252 offset:52224
	ds_read_b128 v[182:185], v252 offset:53248
	ds_read_b128 v[186:189], v252 offset:54272
	ds_read_b128 v[190:193], v252 offset:55296
	ds_read_b128 v[194:197], v252 offset:56320
	global_load_lds_dwordx4 v[78:79], off
	s_add_i32 m0, s36, 0x2000
	s_add_u32 s46, s46, 0x40080
	v_lshl_add_u64 v[78:79], v[200:201], 0, s[80:81]
	s_addc_u32 s47, s47, 0
	s_add_i32 s36, s50, s1
	global_load_lds_dwordx4 v[78:79], off
	v_lshl_add_u64 v[78:79], s[46:47], 0, v[0:1]
	s_mov_b32 m0, s36
	s_nop 0
	global_load_lds_dwordx4 v[78:79], off
	v_lshl_add_u64 v[78:79], s[46:47], 0, v[214:215]
	s_add_i32 m0, s36, 0x2000
	s_nop 0
	global_load_lds_dwordx4 v[78:79], off
	v_lshl_add_u64 v[78:79], v[202:203], 0, s[80:81]
	s_mov_b32 m0, s70
	s_nop 0
	global_load_lds_dwordx4 v[78:79], off
	v_lshl_add_u64 v[78:79], v[204:205], 0, s[80:81]
	s_mov_b32 m0, s71
	s_nop 0
	global_load_lds_dwordx4 v[78:79], off
	s_waitcnt vmcnt(8)
	s_waitcnt lgkmcnt(0)
	s_barrier
	s_setprio 1
	v_mfma_f32_16x16x32_bf16 v[78:81], v[58:61], v[166:169], v[86:89]
	v_mfma_f32_16x16x32_bf16 v[86:89], v[62:65], v[170:173], v[78:81]
	v_mfma_f32_16x16x32_bf16 v[78:81], v[66:69], v[166:169], v[82:85]
	v_mfma_f32_16x16x32_bf16 v[46:49], v[58:61], v[174:177], v[46:49]
	v_mfma_f32_16x16x32_bf16 v[42:45], v[66:69], v[174:177], v[42:45]
	v_mfma_f32_16x16x32_bf16 v[30:33], v[58:61], v[182:185], v[30:33]
	v_mfma_f32_16x16x32_bf16 v[26:29], v[66:69], v[182:185], v[26:29]
	v_mfma_f32_16x16x32_bf16 v[14:17], v[58:61], v[190:193], v[14:17]
	v_mfma_f32_16x16x32_bf16 v[10:13], v[66:69], v[190:193], v[10:13]
	v_mfma_f32_16x16x32_bf16 v[82:85], v[70:73], v[170:173], v[78:81]
	v_mfma_f32_16x16x32_bf16 v[46:49], v[62:65], v[178:181], v[46:49]
	v_mfma_f32_16x16x32_bf16 v[42:45], v[70:73], v[178:181], v[42:45]
	v_mfma_f32_16x16x32_bf16 v[30:33], v[62:65], v[186:189], v[30:33]
	v_mfma_f32_16x16x32_bf16 v[26:29], v[70:73], v[186:189], v[26:29]
	v_mfma_f32_16x16x32_bf16 v[14:17], v[62:65], v[194:197], v[14:17]
	v_mfma_f32_16x16x32_bf16 v[10:13], v[70:73], v[194:197], v[10:13]
	v_mfma_f32_16x16x32_bf16 v[50:53], v[74:77], v[166:169], v[50:53]
	v_mfma_f32_16x16x32_bf16 v[78:81], v[90:93], v[170:173], v[50:53]
	v_mfma_f32_16x16x32_bf16 v[50:53], v[94:97], v[166:169], v[54:57]
	v_mfma_f32_16x16x32_bf16 v[38:41], v[74:77], v[174:177], v[38:41]
	v_mfma_f32_16x16x32_bf16 v[34:37], v[94:97], v[174:177], v[34:37]
	v_mfma_f32_16x16x32_bf16 v[22:25], v[74:77], v[182:185], v[22:25]
	v_mfma_f32_16x16x32_bf16 v[18:21], v[94:97], v[182:185], v[18:21]
	v_mfma_f32_16x16x32_bf16 v[6:9], v[74:77], v[190:193], v[6:9]
	v_mfma_f32_16x16x32_bf16 v[2:5], v[94:97], v[190:193], v[2:5]
	v_mfma_f32_16x16x32_bf16 v[66:69], v[162:165], v[170:173], v[50:53]
	v_mfma_f32_16x16x32_bf16 v[38:41], v[90:93], v[178:181], v[38:41]
	v_mfma_f32_16x16x32_bf16 v[34:37], v[162:165], v[178:181], v[34:37]
	v_mfma_f32_16x16x32_bf16 v[22:25], v[90:93], v[186:189], v[22:25]
	v_mfma_f32_16x16x32_bf16 v[18:21], v[162:165], v[186:189], v[18:21]
	v_mfma_f32_16x16x32_bf16 v[6:9], v[90:93], v[194:197], v[6:9]
	v_mfma_f32_16x16x32_bf16 v[2:5], v[162:165], v[194:197], v[2:5]
	s_setprio 0
	s_barrier
	s_add_i32 s35, s35, 2
	s_add_u32 s4, s4, 0x100
	s_addc_u32 s5, s5, 0
	s_add_u32 s33, s33, 0x100
	s_addc_u32 s34, s34, 0
	s_cmp_gt_u32 s35, 13
	s_cbranch_scc0 .LBB0_1096
	s_and_b64 vcc, exec, s[16:17]
	s_cbranch_vccz .LBB0_1099
	s_barrier

.LBB0_1248:
	s_add_u32 s22, s20, 0xfffc0080
	s_addc_u32 s23, s21, -1
	s_add_i32 s48, 0, 0x10000
	s_cmp_eq_u32 s47, 12
	s_cselect_b32 s25, s13, s23
	s_cselect_b32 s24, s19, s22
	s_cselect_b32 s23, s11, s46
	s_cselect_b32 s22, s44, s45
	s_add_i32 s50, 0, 0x14000
	v_add_u32_e32 v142, s48, v171
	v_add_u32_e32 v164, s50, v171
	ds_read_b128 v[130:133], v142
	ds_read_b128 v[134:137], v142 offset:1024
	ds_read_b128 v[138:141], v142 offset:2048
	ds_read_b128 v[142:145], v142 offset:3072
	ds_read_b128 v[160:163], v164
	ds_read_b128 v[176:179], v164 offset:1024
	ds_read_b128 v[180:183], v164 offset:2048
	ds_read_b128 v[184:187], v164 offset:3072
	v_lshl_add_u64 v[164:165], s[20:21], 0, v[156:157]
	s_add_i32 m0, s31, 0xc000
	ds_read_b128 v[188:191], v175
	ds_read_b128 v[192:195], v175 offset:1024
	ds_read_b128 v[196:199], v175 offset:2048
	ds_read_b128 v[200:203], v175 offset:3072
	ds_read_b128 v[204:207], v175 offset:4096
	ds_read_b128 v[208:211], v175 offset:5120
	ds_read_b128 v[212:215], v175 offset:6144
	ds_read_b128 v[216:219], v175 offset:7168
	global_load_lds_dwordx4 v[164:165], off
	v_lshl_add_u64 v[164:165], s[20:21], 0, v[158:159]
	s_add_i32 m0, s31, 0xe000
	s_nop 0
	global_load_lds_dwordx4 v[164:165], off
	s_waitcnt vmcnt(8)
	s_waitcnt lgkmcnt(0)
	s_barrier
	s_setprio 1
	v_mfma_f32_16x16x32_bf16 v[126:129], v[130:133], v[188:191], v[126:129]
	v_mfma_f32_16x16x32_bf16 v[122:125], v[138:141], v[188:191], v[122:125]
	v_mfma_f32_16x16x32_bf16 v[110:113], v[130:133], v[196:199], v[110:113]
	v_mfma_f32_16x16x32_bf16 v[106:109], v[138:141], v[196:199], v[106:109]
	v_mfma_f32_16x16x32_bf16 v[94:97], v[130:133], v[204:207], v[94:97]
	v_mfma_f32_16x16x32_bf16 v[90:93], v[138:141], v[204:207], v[90:93]
	v_mfma_f32_16x16x32_bf16 v[78:81], v[130:133], v[212:215], v[78:81]
	v_mfma_f32_16x16x32_bf16 v[74:77], v[138:141], v[212:215], v[74:77]
	v_mfma_f32_16x16x32_bf16 v[126:129], v[134:137], v[192:195], v[126:129]
	v_mfma_f32_16x16x32_bf16 v[122:125], v[142:145], v[192:195], v[122:125]
	v_mfma_f32_16x16x32_bf16 v[110:113], v[134:137], v[200:203], v[110:113]
	v_mfma_f32_16x16x32_bf16 v[106:109], v[142:145], v[200:203], v[106:109]
	v_mfma_f32_16x16x32_bf16 v[94:97], v[134:137], v[208:211], v[94:97]
	v_mfma_f32_16x16x32_bf16 v[90:93], v[142:145], v[208:211], v[90:93]
	v_mfma_f32_16x16x32_bf16 v[78:81], v[134:137], v[216:219], v[78:81]
	v_mfma_f32_16x16x32_bf16 v[74:77], v[142:145], v[216:219], v[74:77]
	v_mfma_f32_16x16x32_bf16 v[118:121], v[160:163], v[188:191], v[118:121]
	v_mfma_f32_16x16x32_bf16 v[114:117], v[180:183], v[188:191], v[114:117]
	v_mfma_f32_16x16x32_bf16 v[102:105], v[160:163], v[196:199], v[102:105]
	v_mfma_f32_16x16x32_bf16 v[98:101], v[180:183], v[196:199], v[98:101]
	v_mfma_f32_16x16x32_bf16 v[86:89], v[160:163], v[204:207], v[86:89]
	v_mfma_f32_16x16x32_bf16 v[82:85], v[180:183], v[204:207], v[82:85]
	v_mfma_f32_16x16x32_bf16 v[70:73], v[160:163], v[212:215], v[70:73]
	v_mfma_f32_16x16x32_bf16 v[66:69], v[180:183], v[212:215], v[66:69]
	v_mfma_f32_16x16x32_bf16 v[118:121], v[176:179], v[192:195], v[118:121]
	v_mfma_f32_16x16x32_bf16 v[114:117], v[184:187], v[192:195], v[114:117]
	v_mfma_f32_16x16x32_bf16 v[102:105], v[176:179], v[200:203], v[102:105]
	v_mfma_f32_16x16x32_bf16 v[98:101], v[184:187], v[200:203], v[98:101]
	v_mfma_f32_16x16x32_bf16 v[86:89], v[176:179], v[208:211], v[86:89]
	v_mfma_f32_16x16x32_bf16 v[82:85], v[184:187], v[208:211], v[82:85]
	v_mfma_f32_16x16x32_bf16 v[70:73], v[176:179], v[216:219], v[70:73]
	v_mfma_f32_16x16x32_bf16 v[66:69], v[184:187], v[216:219], v[66:69]
	s_setprio 0
	s_barrier
	s_add_i32 s48, s48, s30
	v_lshl_add_u64 v[164:165], s[22:23], 0, v[0:1]
	s_mov_b32 m0, s48
	ds_read_b128 v[188:191], v175 offset:16384
	ds_read_b128 v[192:195], v175 offset:17408
	ds_read_b128 v[196:199], v175 offset:18432
	ds_read_b128 v[200:203], v175 offset:19456
	ds_read_b128 v[204:207], v175 offset:20480
	ds_read_b128 v[208:211], v175 offset:21504
	ds_read_b128 v[212:215], v175 offset:22528
	ds_read_b128 v[216:219], v175 offset:23552
	global_load_lds_dwordx4 v[164:165], off
	s_add_i32 m0, s48, 0x2000
	s_add_u32 s48, s22, 0x40000
	v_lshl_add_u64 v[168:169], s[22:23], 0, v[146:147]
	s_addc_u32 s49, s23, 0
	s_add_i32 s50, s50, s30
	global_load_lds_dwordx4 v[168:169], off
	v_lshl_add_u64 v[172:173], s[48:49], 0, v[0:1]
	s_mov_b32 m0, s50
	v_lshl_add_u64 v[220:221], s[24:25], 0, v[148:149]
	global_load_lds_dwordx4 v[172:173], off
	v_lshl_add_u64 v[172:173], s[48:49], 0, v[146:147]
	s_add_i32 m0, s50, 0x2000
	s_nop 0
	global_load_lds_dwordx4 v[172:173], off
	v_lshl_add_u64 v[172:173], s[24:25], 0, v[150:151]
	s_mov_b32 m0, s31
	s_nop 0
	global_load_lds_dwordx4 v[172:173], off
	s_mov_b32 m0, s33
	s_nop 0
	global_load_lds_dwordx4 v[220:221], off
	s_waitcnt vmcnt(8)
	s_waitcnt lgkmcnt(0)
	s_barrier
	s_setprio 1
	v_mfma_f32_16x16x32_bf16 v[62:65], v[130:133], v[188:191], v[62:65]
	v_mfma_f32_16x16x32_bf16 v[58:61], v[138:141], v[188:191], v[58:61]
	v_mfma_f32_16x16x32_bf16 v[46:49], v[130:133], v[196:199], v[46:49]
	v_mfma_f32_16x16x32_bf16 v[42:45], v[138:141], v[196:199], v[42:45]
	v_mfma_f32_16x16x32_bf16 v[30:33], v[130:133], v[204:207], v[30:33]
	v_mfma_f32_16x16x32_bf16 v[26:29], v[138:141], v[204:207], v[26:29]
	v_mfma_f32_16x16x32_bf16 v[14:17], v[130:133], v[212:215], v[14:17]
	v_mfma_f32_16x16x32_bf16 v[10:13], v[138:141], v[212:215], v[10:13]
	v_mfma_f32_16x16x32_bf16 v[62:65], v[134:137], v[192:195], v[62:65]
	v_mfma_f32_16x16x32_bf16 v[58:61], v[142:145], v[192:195], v[58:61]
	v_mfma_f32_16x16x32_bf16 v[46:49], v[134:137], v[200:203], v[46:49]
	v_mfma_f32_16x16x32_bf16 v[42:45], v[142:145], v[200:203], v[42:45]
	v_mfma_f32_16x16x32_bf16 v[30:33], v[134:137], v[208:211], v[30:33]
	v_mfma_f32_16x16x32_bf16 v[26:29], v[142:145], v[208:211], v[26:29]
	v_mfma_f32_16x16x32_bf16 v[14:17], v[134:137], v[216:219], v[14:17]
	v_mfma_f32_16x16x32_bf16 v[10:13], v[142:145], v[216:219], v[10:13]
	v_mfma_f32_16x16x32_bf16 v[54:57], v[160:163], v[188:191], v[54:57]
	v_mfma_f32_16x16x32_bf16 v[50:53], v[180:183], v[188:191], v[50:53]
	v_mfma_f32_16x16x32_bf16 v[38:41], v[160:163], v[196:199], v[38:41]
	v_mfma_f32_16x16x32_bf16 v[34:37], v[180:183], v[196:199], v[34:37]
	v_mfma_f32_16x16x32_bf16 v[22:25], v[160:163], v[204:207], v[22:25]
	v_mfma_f32_16x16x32_bf16 v[18:21], v[180:183], v[204:207], v[18:21]
	v_mfma_f32_16x16x32_bf16 v[6:9], v[160:163], v[212:215], v[6:9]
	v_mfma_f32_16x16x32_bf16 v[2:5], v[180:183], v[212:215], v[2:5]
	v_mfma_f32_16x16x32_bf16 v[54:57], v[176:179], v[192:195], v[54:57]
	v_mfma_f32_16x16x32_bf16 v[50:53], v[184:187], v[192:195], v[50:53]
	v_mfma_f32_16x16x32_bf16 v[38:41], v[176:179], v[200:203], v[38:41]
	v_mfma_f32_16x16x32_bf16 v[34:37], v[184:187], v[200:203], v[34:37]
	v_mfma_f32_16x16x32_bf16 v[22:25], v[176:179], v[208:211], v[22:25]
	v_mfma_f32_16x16x32_bf16 v[18:21], v[184:187], v[208:211], v[18:21]
	v_mfma_f32_16x16x32_bf16 v[6:9], v[176:179], v[216:219], v[6:9]
	v_mfma_f32_16x16x32_bf16 v[2:5], v[184:187], v[216:219], v[2:5]
	s_setprio 0
	s_barrier
	s_add_i32 s48, 0, 0x18000
	s_add_i32 s49, 0, 0x1c000
	v_add_u32_e32 v142, s48, v171
	v_add_u32_e32 v166, s49, v171
	ds_read_b128 v[130:133], v142
	ds_read_b128 v[134:137], v142 offset:1024
	ds_read_b128 v[138:141], v142 offset:2048
	ds_read_b128 v[142:145], v142 offset:3072
	ds_read_b128 v[160:163], v166
	ds_read_b128 v[176:179], v166 offset:1024
	ds_read_b128 v[180:183], v166 offset:2048
	ds_read_b128 v[184:187], v166 offset:3072
	s_add_u32 s24, s24, 0x40000
	s_addc_u32 s25, s25, 0
	s_mov_b32 m0, s34
	v_lshl_add_u64 v[222:223], s[24:25], 0, v[150:151]
	ds_read_b128 v[188:191], v175 offset:32768
	ds_read_b128 v[192:195], v175 offset:33792
	ds_read_b128 v[196:199], v175 offset:34816
	ds_read_b128 v[200:203], v175 offset:35840
	ds_read_b128 v[204:207], v175 offset:36864
	ds_read_b128 v[208:211], v175 offset:37888
	ds_read_b128 v[212:215], v175 offset:38912
	ds_read_b128 v[216:219], v175 offset:39936
	global_load_lds_dwordx4 v[222:223], off
	v_lshl_add_u64 v[222:223], s[24:25], 0, v[148:149]
	s_mov_b32 m0, s35
	s_nop 0
	global_load_lds_dwordx4 v[222:223], off
	s_waitcnt vmcnt(8)
	s_waitcnt lgkmcnt(0)
	s_barrier
	s_setprio 1
	v_mfma_f32_16x16x32_bf16 v[126:129], v[130:133], v[188:191], v[126:129]
	v_mfma_f32_16x16x32_bf16 v[122:125], v[138:141], v[188:191], v[122:125]
	v_mfma_f32_16x16x32_bf16 v[110:113], v[130:133], v[196:199], v[110:113]
	v_mfma_f32_16x16x32_bf16 v[106:109], v[138:141], v[196:199], v[106:109]
	v_mfma_f32_16x16x32_bf16 v[94:97], v[130:133], v[204:207], v[94:97]
	v_mfma_f32_16x16x32_bf16 v[90:93], v[138:141], v[204:207], v[90:93]
	v_mfma_f32_16x16x32_bf16 v[78:81], v[130:133], v[212:215], v[78:81]
	v_mfma_f32_16x16x32_bf16 v[74:77], v[138:141], v[212:215], v[74:77]
	v_mfma_f32_16x16x32_bf16 v[126:129], v[134:137], v[192:195], v[126:129]
	v_mfma_f32_16x16x32_bf16 v[122:125], v[142:145], v[192:195], v[122:125]
	v_mfma_f32_16x16x32_bf16 v[110:113], v[134:137], v[200:203], v[110:113]
	v_mfma_f32_16x16x32_bf16 v[106:109], v[142:145], v[200:203], v[106:109]
	v_mfma_f32_16x16x32_bf16 v[94:97], v[134:137], v[208:211], v[94:97]
	v_mfma_f32_16x16x32_bf16 v[90:93], v[142:145], v[208:211], v[90:93]
	v_mfma_f32_16x16x32_bf16 v[78:81], v[134:137], v[216:219], v[78:81]
	v_mfma_f32_16x16x32_bf16 v[74:77], v[142:145], v[216:219], v[74:77]
	v_mfma_f32_16x16x32_bf16 v[118:121], v[160:163], v[188:191], v[118:121]
	v_mfma_f32_16x16x32_bf16 v[114:117], v[180:183], v[188:191], v[114:117]
	v_mfma_f32_16x16x32_bf16 v[102:105], v[160:163], v[196:199], v[102:105]
	v_mfma_f32_16x16x32_bf16 v[98:101], v[180:183], v[196:199], v[98:101]
	v_mfma_f32_16x16x32_bf16 v[86:89], v[160:163], v[204:207], v[86:89]
	v_mfma_f32_16x16x32_bf16 v[82:85], v[180:183], v[204:207], v[82:85]
	v_mfma_f32_16x16x32_bf16 v[70:73], v[160:163], v[212:215], v[70:73]
	v_mfma_f32_16x16x32_bf16 v[66:69], v[180:183], v[212:215], v[66:69]
	v_mfma_f32_16x16x32_bf16 v[118:121], v[176:179], v[192:195], v[118:121]
	v_mfma_f32_16x16x32_bf16 v[114:117], v[184:187], v[192:195], v[114:117]
	v_mfma_f32_16x16x32_bf16 v[102:105], v[176:179], v[200:203], v[102:105]
	v_mfma_f32_16x16x32_bf16 v[98:101], v[184:187], v[200:203], v[98:101]
	v_mfma_f32_16x16x32_bf16 v[86:89], v[176:179], v[208:211], v[86:89]
	v_mfma_f32_16x16x32_bf16 v[82:85], v[184:187], v[208:211], v[82:85]
	v_mfma_f32_16x16x32_bf16 v[70:73], v[176:179], v[216:219], v[70:73]
	v_mfma_f32_16x16x32_bf16 v[66:69], v[184:187], v[216:219], v[66:69]
	s_setprio 0
	s_barrier
	s_add_i32 s24, s48, s30
	v_lshl_add_u64 v[164:165], v[164:165], 0, s[80:81]
	s_mov_b32 m0, s24
	ds_read_b128 v[188:191], v175 offset:49152
	ds_read_b128 v[192:195], v175 offset:50176
	ds_read_b128 v[196:199], v175 offset:51200
	ds_read_b128 v[200:203], v175 offset:52224
	ds_read_b128 v[204:207], v175 offset:53248
	ds_read_b128 v[208:211], v175 offset:54272
	ds_read_b128 v[212:215], v175 offset:55296
	ds_read_b128 v[216:219], v175 offset:56320
	global_load_lds_dwordx4 v[164:165], off
	s_add_i32 m0, s24, 0x2000
	s_add_u32 s22, s22, 0x40080
	v_lshl_add_u64 v[164:165], v[168:169], 0, s[80:81]
	s_addc_u32 s23, s23, 0
	s_add_i32 s24, s49, s30
	global_load_lds_dwordx4 v[164:165], off
	v_lshl_add_u64 v[164:165], s[22:23], 0, v[0:1]
	s_mov_b32 m0, s24
	s_nop 0
	global_load_lds_dwordx4 v[164:165], off
	v_lshl_add_u64 v[164:165], s[22:23], 0, v[146:147]
	s_add_i32 m0, s24, 0x2000
	s_nop 0
	global_load_lds_dwordx4 v[164:165], off
	v_lshl_add_u64 v[164:165], v[172:173], 0, s[80:81]
	s_mov_b32 m0, s41
	s_nop 0
	global_load_lds_dwordx4 v[164:165], off
	v_lshl_add_u64 v[164:165], v[220:221], 0, s[80:81]
	s_mov_b32 m0, s42
	s_nop 0
	global_load_lds_dwordx4 v[164:165], off
	s_waitcnt vmcnt(8)
	s_waitcnt lgkmcnt(0)
	s_barrier
	s_setprio 1
	v_mfma_f32_16x16x32_bf16 v[62:65], v[130:133], v[188:191], v[62:65]
	v_mfma_f32_16x16x32_bf16 v[58:61], v[138:141], v[188:191], v[58:61]
	v_mfma_f32_16x16x32_bf16 v[46:49], v[130:133], v[196:199], v[46:49]
	v_mfma_f32_16x16x32_bf16 v[42:45], v[138:141], v[196:199], v[42:45]
	v_mfma_f32_16x16x32_bf16 v[30:33], v[130:133], v[204:207], v[30:33]
	v_mfma_f32_16x16x32_bf16 v[26:29], v[138:141], v[204:207], v[26:29]
	v_mfma_f32_16x16x32_bf16 v[14:17], v[130:133], v[212:215], v[14:17]
	v_mfma_f32_16x16x32_bf16 v[10:13], v[138:141], v[212:215], v[10:13]
	v_mfma_f32_16x16x32_bf16 v[62:65], v[134:137], v[192:195], v[62:65]
	v_mfma_f32_16x16x32_bf16 v[58:61], v[142:145], v[192:195], v[58:61]
	v_mfma_f32_16x16x32_bf16 v[46:49], v[134:137], v[200:203], v[46:49]
	v_mfma_f32_16x16x32_bf16 v[42:45], v[142:145], v[200:203], v[42:45]
	v_mfma_f32_16x16x32_bf16 v[30:33], v[134:137], v[208:211], v[30:33]
	v_mfma_f32_16x16x32_bf16 v[26:29], v[142:145], v[208:211], v[26:29]
	v_mfma_f32_16x16x32_bf16 v[14:17], v[134:137], v[216:219], v[14:17]
	v_mfma_f32_16x16x32_bf16 v[10:13], v[142:145], v[216:219], v[10:13]
	v_mfma_f32_16x16x32_bf16 v[54:57], v[160:163], v[188:191], v[54:57]
	v_mfma_f32_16x16x32_bf16 v[50:53], v[180:183], v[188:191], v[50:53]
	v_mfma_f32_16x16x32_bf16 v[38:41], v[160:163], v[196:199], v[38:41]
	v_mfma_f32_16x16x32_bf16 v[34:37], v[180:183], v[196:199], v[34:37]
	v_mfma_f32_16x16x32_bf16 v[22:25], v[160:163], v[204:207], v[22:25]
	v_mfma_f32_16x16x32_bf16 v[18:21], v[180:183], v[204:207], v[18:21]
	v_mfma_f32_16x16x32_bf16 v[6:9], v[160:163], v[212:215], v[6:9]
	v_mfma_f32_16x16x32_bf16 v[2:5], v[180:183], v[212:215], v[2:5]
	v_mfma_f32_16x16x32_bf16 v[54:57], v[176:179], v[192:195], v[54:57]
	v_mfma_f32_16x16x32_bf16 v[50:53], v[184:187], v[192:195], v[50:53]
	v_mfma_f32_16x16x32_bf16 v[38:41], v[176:179], v[200:203], v[38:41]
	v_mfma_f32_16x16x32_bf16 v[34:37], v[184:187], v[200:203], v[34:37]
	v_mfma_f32_16x16x32_bf16 v[22:25], v[176:179], v[208:211], v[22:25]
	v_mfma_f32_16x16x32_bf16 v[18:21], v[184:187], v[208:211], v[18:21]
	v_mfma_f32_16x16x32_bf16 v[6:9], v[176:179], v[216:219], v[6:9]
	v_mfma_f32_16x16x32_bf16 v[2:5], v[184:187], v[216:219], v[2:5]
	s_setprio 0
	s_barrier
	s_add_i32 s47, s47, 2
	s_add_u32 s20, s20, 0x100
	s_addc_u32 s21, s21, 0
	s_add_u32 s45, s45, 0x100
	s_addc_u32 s46, s46, 0
	s_cmp_gt_u32 s47, 13
	s_cbranch_scc0 .LBB0_1248
	s_and_b64 vcc, exec, s[6:7]
	s_cbranch_vccz .LBB0_1251
	s_barrier

.LBB0_1325:
	s_add_u32 s8, s6, 0xfffc0080
	s_addc_u32 s9, s7, -1
	s_add_i32 s46, 0, 0x10000
	s_cmp_eq_u32 s39, 12
	s_cselect_b32 s11, s12, s9
	s_cselect_b32 s10, s13, s8
	s_cselect_b32 s9, s14, s35
	s_cselect_b32 s8, s15, s31
	s_add_i32 s58, 0, 0x14000
	v_add_u32_e32 v14, s46, v207
	v_add_u32_e32 v30, s58, v207
	ds_read_b128 v[2:5], v14
	ds_read_b128 v[6:9], v14 offset:1024
	ds_read_b128 v[10:13], v14 offset:2048
	ds_read_b128 v[14:17], v14 offset:3072
	ds_read_b128 v[18:21], v30
	ds_read_b128 v[22:25], v30 offset:1024
	ds_read_b128 v[26:29], v30 offset:2048
	ds_read_b128 v[30:33], v30 offset:3072
	v_lshl_add_u64 v[214:215], s[6:7], 0, v[186:187]
	s_add_i32 m0, s62, 0xc000
	ds_read_b128 v[66:69], v213
	ds_read_b128 v[70:73], v213 offset:1024
	ds_read_b128 v[82:85], v213 offset:2048
	ds_read_b128 v[86:89], v213 offset:3072
	ds_read_b128 v[190:193], v213 offset:4096
	ds_read_b128 v[194:197], v213 offset:5120
	ds_read_b128 v[198:201], v213 offset:6144
	ds_read_b128 v[202:205], v213 offset:7168
	global_load_lds_dwordx4 v[214:215], off
	v_lshl_add_u64 v[214:215], s[6:7], 0, v[188:189]
	s_add_i32 m0, s62, 0xe000
	s_nop 0
	global_load_lds_dwordx4 v[214:215], off
	s_waitcnt vmcnt(8)
	s_waitcnt lgkmcnt(0)
	s_barrier
	s_setprio 1
	v_mfma_f32_16x16x32_bf16 v[174:177], v[2:5], v[66:69], v[174:177]
	v_mfma_f32_16x16x32_bf16 v[170:173], v[10:13], v[66:69], v[170:173]
	v_mfma_f32_16x16x32_bf16 v[158:161], v[2:5], v[82:85], v[158:161]
	v_mfma_f32_16x16x32_bf16 v[154:157], v[10:13], v[82:85], v[154:157]
	v_mfma_f32_16x16x32_bf16 v[142:145], v[2:5], v[190:193], v[142:145]
	v_mfma_f32_16x16x32_bf16 v[138:141], v[10:13], v[190:193], v[138:141]
	v_mfma_f32_16x16x32_bf16 v[126:129], v[2:5], v[198:201], v[126:129]
	v_mfma_f32_16x16x32_bf16 v[122:125], v[10:13], v[198:201], v[122:125]
	v_mfma_f32_16x16x32_bf16 v[174:177], v[6:9], v[70:73], v[174:177]
	v_mfma_f32_16x16x32_bf16 v[170:173], v[14:17], v[70:73], v[170:173]
	v_mfma_f32_16x16x32_bf16 v[158:161], v[6:9], v[86:89], v[158:161]
	v_mfma_f32_16x16x32_bf16 v[154:157], v[14:17], v[86:89], v[154:157]
	v_mfma_f32_16x16x32_bf16 v[142:145], v[6:9], v[194:197], v[142:145]
	v_mfma_f32_16x16x32_bf16 v[138:141], v[14:17], v[194:197], v[138:141]
	v_mfma_f32_16x16x32_bf16 v[126:129], v[6:9], v[202:205], v[126:129]
	v_mfma_f32_16x16x32_bf16 v[122:125], v[14:17], v[202:205], v[122:125]
	v_mfma_f32_16x16x32_bf16 v[166:169], v[18:21], v[66:69], v[166:169]
	v_mfma_f32_16x16x32_bf16 v[66:69], v[26:29], v[66:69], v[162:165]
	v_mfma_f32_16x16x32_bf16 v[166:169], v[22:25], v[70:73], v[166:169]
	v_mfma_f32_16x16x32_bf16 v[66:69], v[30:33], v[70:73], v[66:69]
	v_mfma_f32_16x16x32_bf16 v[70:73], v[18:21], v[82:85], v[150:153]
	v_mfma_f32_16x16x32_bf16 v[82:85], v[26:29], v[82:85], v[146:149]
	v_mfma_f32_16x16x32_bf16 v[130:133], v[26:29], v[190:193], v[130:133]
	v_mfma_f32_16x16x32_bf16 v[118:121], v[18:21], v[198:201], v[118:121]
	v_mfma_f32_16x16x32_bf16 v[114:117], v[26:29], v[198:201], v[114:117]
	v_mfma_f32_16x16x32_bf16 v[70:73], v[22:25], v[86:89], v[70:73]
	v_mfma_f32_16x16x32_bf16 v[82:85], v[30:33], v[86:89], v[82:85]
	v_mfma_f32_16x16x32_bf16 v[86:89], v[18:21], v[190:193], v[134:137]
	v_mfma_f32_16x16x32_bf16 v[130:133], v[30:33], v[194:197], v[130:133]
	v_mfma_f32_16x16x32_bf16 v[118:121], v[22:25], v[202:205], v[118:121]
	v_mfma_f32_16x16x32_bf16 v[114:117], v[30:33], v[202:205], v[114:117]
	v_mfma_f32_16x16x32_bf16 v[86:89], v[22:25], v[194:197], v[86:89]
	s_setprio 0
	s_barrier
	s_add_i32 s46, s46, s57
	v_lshl_add_u64 v[230:231], s[8:9], 0, v[0:1]
	s_mov_b32 m0, s46
	ds_read_b128 v[134:137], v213 offset:16384
	ds_read_b128 v[146:149], v213 offset:17408
	ds_read_b128 v[150:153], v213 offset:18432
	ds_read_b128 v[162:165], v213 offset:19456
	ds_read_b128 v[190:193], v213 offset:20480
	ds_read_b128 v[194:197], v213 offset:21504
	ds_read_b128 v[198:201], v213 offset:22528
	ds_read_b128 v[202:205], v213 offset:23552
	global_load_lds_dwordx4 v[230:231], off
	s_add_i32 m0, s46, 0x2000
	s_add_u32 s46, s8, 0x40000
	v_lshl_add_u64 v[232:233], s[8:9], 0, v[178:179]
	s_addc_u32 s47, s9, 0
	s_add_i32 s58, s58, s57
	global_load_lds_dwordx4 v[232:233], off
	v_lshl_add_u64 v[214:215], s[46:47], 0, v[0:1]
	s_mov_b32 m0, s58
	v_lshl_add_u64 v[234:235], s[10:11], 0, v[182:183]
	global_load_lds_dwordx4 v[214:215], off
	v_lshl_add_u64 v[214:215], s[46:47], 0, v[178:179]
	s_add_i32 m0, s58, 0x2000
	v_lshl_add_u64 v[236:237], s[10:11], 0, v[180:181]
	global_load_lds_dwordx4 v[214:215], off
	s_mov_b32 m0, s62
	s_nop 0
	global_load_lds_dwordx4 v[234:235], off
	s_mov_b32 m0, s63
	s_nop 0
	global_load_lds_dwordx4 v[236:237], off
	s_waitcnt vmcnt(8)
	s_waitcnt lgkmcnt(0)
	s_barrier
	s_setprio 1
	v_mfma_f32_16x16x32_bf16 v[110:113], v[2:5], v[134:137], v[110:113]
	v_mfma_f32_16x16x32_bf16 v[106:109], v[10:13], v[134:137], v[106:109]
	v_mfma_f32_16x16x32_bf16 v[94:97], v[2:5], v[150:153], v[94:97]
	v_mfma_f32_16x16x32_bf16 v[90:93], v[10:13], v[150:153], v[90:93]
	v_mfma_f32_16x16x32_bf16 v[62:65], v[2:5], v[190:193], v[62:65]
	v_mfma_f32_16x16x32_bf16 v[58:61], v[10:13], v[190:193], v[58:61]
	v_mfma_f32_16x16x32_bf16 v[2:5], v[2:5], v[198:201], v[46:49]
	v_mfma_f32_16x16x32_bf16 v[110:113], v[6:9], v[146:149], v[110:113]
	v_mfma_f32_16x16x32_bf16 v[106:109], v[14:17], v[146:149], v[106:109]
	v_mfma_f32_16x16x32_bf16 v[94:97], v[6:9], v[162:165], v[94:97]
	v_mfma_f32_16x16x32_bf16 v[90:93], v[14:17], v[162:165], v[90:93]
	v_mfma_f32_16x16x32_bf16 v[62:65], v[6:9], v[194:197], v[62:65]
	v_mfma_f32_16x16x32_bf16 v[58:61], v[14:17], v[194:197], v[58:61]
	v_mfma_f32_16x16x32_bf16 v[2:5], v[6:9], v[202:205], v[2:5]
	v_mfma_f32_16x16x32_bf16 v[6:9], v[10:13], v[198:201], v[42:45]
	v_mfma_f32_16x16x32_bf16 v[6:9], v[14:17], v[202:205], v[6:9]
	v_mfma_f32_16x16x32_bf16 v[42:45], v[18:21], v[150:153], v[78:81]
	v_mfma_f32_16x16x32_bf16 v[78:81], v[22:25], v[162:165], v[42:45]
	v_mfma_f32_16x16x32_bf16 v[42:45], v[26:29], v[150:153], v[74:77]
	v_mfma_f32_16x16x32_bf16 v[74:77], v[30:33], v[162:165], v[42:45]
	v_mfma_f32_16x16x32_bf16 v[42:45], v[18:21], v[190:193], v[54:57]
	v_mfma_f32_16x16x32_bf16 v[10:13], v[18:21], v[134:137], v[102:105]
	v_mfma_f32_16x16x32_bf16 v[54:57], v[22:25], v[194:197], v[42:45]
	v_mfma_f32_16x16x32_bf16 v[42:45], v[26:29], v[190:193], v[50:53]
	v_mfma_f32_16x16x32_bf16 v[18:21], v[18:21], v[198:201], v[38:41]
	v_mfma_f32_16x16x32_bf16 v[10:13], v[22:25], v[146:149], v[10:13]
	v_mfma_f32_16x16x32_bf16 v[14:17], v[26:29], v[134:137], v[98:101]
	v_mfma_f32_16x16x32_bf16 v[50:53], v[30:33], v[194:197], v[42:45]
	v_mfma_f32_16x16x32_bf16 v[18:21], v[22:25], v[202:205], v[18:21]
	v_mfma_f32_16x16x32_bf16 v[22:25], v[26:29], v[198:201], v[34:37]
	v_mfma_f32_16x16x32_bf16 v[14:17], v[30:33], v[146:149], v[14:17]
	v_mfma_f32_16x16x32_bf16 v[22:25], v[30:33], v[202:205], v[22:25]
	s_setprio 0
	s_barrier
	s_add_i32 s46, 0, 0x18000
	s_add_i32 s47, 0, 0x1c000
	v_add_u32_e32 v38, s46, v207
	v_add_u32_e32 v42, s47, v207
	ds_read_b128 v[26:29], v38
	ds_read_b128 v[30:33], v38 offset:1024
	ds_read_b128 v[34:37], v38 offset:2048
	ds_read_b128 v[38:41], v38 offset:3072
	ds_read_b128 v[190:193], v42
	ds_read_b128 v[194:197], v42 offset:1024
	ds_read_b128 v[198:201], v42 offset:2048
	ds_read_b128 v[202:205], v42 offset:3072
	s_add_u32 s10, s10, 0x40000
	s_addc_u32 s11, s11, 0
	s_mov_b32 m0, s64
	v_lshl_add_u64 v[134:135], s[10:11], 0, v[182:183]
	ds_read_b128 v[42:45], v213 offset:32768
	ds_read_b128 v[46:49], v213 offset:33792
	ds_read_b128 v[98:101], v213 offset:34816
	ds_read_b128 v[102:105], v213 offset:35840
	ds_read_b128 v[214:217], v213 offset:36864
	ds_read_b128 v[218:221], v213 offset:37888
	ds_read_b128 v[222:225], v213 offset:38912
	ds_read_b128 v[226:229], v213 offset:39936
	global_load_lds_dwordx4 v[134:135], off
	v_lshl_add_u64 v[134:135], s[10:11], 0, v[180:181]
	s_mov_b32 m0, s65
	s_nop 0
	global_load_lds_dwordx4 v[134:135], off
	s_waitcnt vmcnt(8)
	s_waitcnt lgkmcnt(0)
	s_barrier
	s_setprio 1
	v_mfma_f32_16x16x32_bf16 v[134:137], v[26:29], v[42:45], v[174:177]
	v_mfma_f32_16x16x32_bf16 v[174:177], v[30:33], v[46:49], v[134:137]
	v_mfma_f32_16x16x32_bf16 v[134:137], v[34:37], v[42:45], v[170:173]
	v_mfma_f32_16x16x32_bf16 v[170:173], v[38:41], v[46:49], v[134:137]
	v_mfma_f32_16x16x32_bf16 v[134:137], v[26:29], v[98:101], v[158:161]
	v_mfma_f32_16x16x32_bf16 v[158:161], v[30:33], v[102:105], v[134:137]
	v_mfma_f32_16x16x32_bf16 v[134:137], v[34:37], v[98:101], v[154:157]
	v_mfma_f32_16x16x32_bf16 v[154:157], v[38:41], v[102:105], v[134:137]
	v_mfma_f32_16x16x32_bf16 v[134:137], v[26:29], v[214:217], v[142:145]
	v_mfma_f32_16x16x32_bf16 v[142:145], v[30:33], v[218:221], v[134:137]
	v_mfma_f32_16x16x32_bf16 v[134:137], v[34:37], v[214:217], v[138:141]
	v_mfma_f32_16x16x32_bf16 v[126:129], v[26:29], v[222:225], v[126:129]
	v_mfma_f32_16x16x32_bf16 v[122:125], v[34:37], v[222:225], v[122:125]
	v_mfma_f32_16x16x32_bf16 v[138:141], v[38:41], v[218:221], v[134:137]
	v_mfma_f32_16x16x32_bf16 v[126:129], v[30:33], v[226:229], v[126:129]
	v_mfma_f32_16x16x32_bf16 v[122:125], v[38:41], v[226:229], v[122:125]
	v_mfma_f32_16x16x32_bf16 v[134:137], v[190:193], v[42:45], v[166:169]
	v_mfma_f32_16x16x32_bf16 v[42:45], v[198:201], v[42:45], v[66:69]
	v_mfma_f32_16x16x32_bf16 v[162:165], v[202:205], v[46:49], v[42:45]
	v_mfma_f32_16x16x32_bf16 v[42:45], v[190:193], v[98:101], v[70:73]
	v_mfma_f32_16x16x32_bf16 v[150:153], v[194:197], v[102:105], v[42:45]
	v_mfma_f32_16x16x32_bf16 v[42:45], v[198:201], v[98:101], v[82:85]
	v_mfma_f32_16x16x32_bf16 v[146:149], v[202:205], v[102:105], v[42:45]
	v_mfma_f32_16x16x32_bf16 v[42:45], v[190:193], v[214:217], v[86:89]
	v_mfma_f32_16x16x32_bf16 v[166:169], v[194:197], v[46:49], v[134:137]
	v_mfma_f32_16x16x32_bf16 v[134:137], v[194:197], v[218:221], v[42:45]
	v_mfma_f32_16x16x32_bf16 v[42:45], v[198:201], v[214:217], v[130:133]
	v_mfma_f32_16x16x32_bf16 v[130:133], v[202:205], v[218:221], v[42:45]
	v_mfma_f32_16x16x32_bf16 v[42:45], v[190:193], v[222:225], v[118:121]
	v_mfma_f32_16x16x32_bf16 v[118:121], v[194:197], v[226:229], v[42:45]
	v_mfma_f32_16x16x32_bf16 v[42:45], v[198:201], v[222:225], v[114:117]
	v_mfma_f32_16x16x32_bf16 v[114:117], v[202:205], v[226:229], v[42:45]
	s_setprio 0
	s_barrier
	s_add_i32 s10, s46, s57
	s_nop 3
	v_lshl_add_u64 v[42:43], v[230:231], 0, s[80:81]
	s_mov_b32 m0, s10
	ds_read_b128 v[66:69], v213 offset:49152
	ds_read_b128 v[70:73], v213 offset:50176
	ds_read_b128 v[82:85], v213 offset:51200
	ds_read_b128 v[86:89], v213 offset:52224
	ds_read_b128 v[214:217], v213 offset:53248
	ds_read_b128 v[218:221], v213 offset:54272
	ds_read_b128 v[222:225], v213 offset:55296
	ds_read_b128 v[226:229], v213 offset:56320
	global_load_lds_dwordx4 v[42:43], off
	s_add_i32 m0, s10, 0x2000
	s_add_u32 s8, s8, 0x40080
	v_lshl_add_u64 v[42:43], v[232:233], 0, s[80:81]
	s_addc_u32 s9, s9, 0
	s_add_i32 s10, s47, s57
	global_load_lds_dwordx4 v[42:43], off
	v_lshl_add_u64 v[42:43], s[8:9], 0, v[0:1]
	s_mov_b32 m0, s10
	s_nop 0
	global_load_lds_dwordx4 v[42:43], off
	v_lshl_add_u64 v[42:43], s[8:9], 0, v[178:179]
	s_add_i32 m0, s10, 0x2000
	s_nop 0
	global_load_lds_dwordx4 v[42:43], off
	v_lshl_add_u64 v[42:43], v[234:235], 0, s[80:81]
	s_mov_b32 m0, s1
	s_nop 0
	global_load_lds_dwordx4 v[42:43], off
	v_lshl_add_u64 v[42:43], v[236:237], 0, s[80:81]
	s_mov_b32 m0, s68
	s_nop 0
	global_load_lds_dwordx4 v[42:43], off
	s_waitcnt vmcnt(8)
	s_waitcnt lgkmcnt(0)
	s_barrier
	s_setprio 1
	v_mfma_f32_16x16x32_bf16 v[42:45], v[26:29], v[66:69], v[110:113]
	v_mfma_f32_16x16x32_bf16 v[110:113], v[30:33], v[70:73], v[42:45]
	v_mfma_f32_16x16x32_bf16 v[42:45], v[34:37], v[66:69], v[106:109]
	v_mfma_f32_16x16x32_bf16 v[106:109], v[38:41], v[70:73], v[42:45]
	v_mfma_f32_16x16x32_bf16 v[42:45], v[26:29], v[82:85], v[94:97]
	v_mfma_f32_16x16x32_bf16 v[94:97], v[30:33], v[86:89], v[42:45]
	v_mfma_f32_16x16x32_bf16 v[42:45], v[34:37], v[82:85], v[90:93]
	v_mfma_f32_16x16x32_bf16 v[90:93], v[38:41], v[86:89], v[42:45]
	v_mfma_f32_16x16x32_bf16 v[42:45], v[26:29], v[214:217], v[62:65]
	v_mfma_f32_16x16x32_bf16 v[2:5], v[26:29], v[222:225], v[2:5]
	v_mfma_f32_16x16x32_bf16 v[62:65], v[30:33], v[218:221], v[42:45]
	v_mfma_f32_16x16x32_bf16 v[42:45], v[34:37], v[214:217], v[58:61]
	v_mfma_f32_16x16x32_bf16 v[46:49], v[30:33], v[226:229], v[2:5]
	v_mfma_f32_16x16x32_bf16 v[2:5], v[34:37], v[222:225], v[6:9]
	v_mfma_f32_16x16x32_bf16 v[58:61], v[38:41], v[218:221], v[42:45]
	v_mfma_f32_16x16x32_bf16 v[42:45], v[38:41], v[226:229], v[2:5]
	v_mfma_f32_16x16x32_bf16 v[2:5], v[190:193], v[66:69], v[10:13]
	v_mfma_f32_16x16x32_bf16 v[102:105], v[194:197], v[70:73], v[2:5]
	v_mfma_f32_16x16x32_bf16 v[2:5], v[198:201], v[66:69], v[14:17]
	v_mfma_f32_16x16x32_bf16 v[98:101], v[202:205], v[70:73], v[2:5]
	v_mfma_f32_16x16x32_bf16 v[2:5], v[190:193], v[82:85], v[78:81]
	v_mfma_f32_16x16x32_bf16 v[78:81], v[194:197], v[86:89], v[2:5]
	v_mfma_f32_16x16x32_bf16 v[2:5], v[198:201], v[82:85], v[74:77]
	v_mfma_f32_16x16x32_bf16 v[74:77], v[202:205], v[86:89], v[2:5]
	v_mfma_f32_16x16x32_bf16 v[2:5], v[190:193], v[214:217], v[54:57]
	v_mfma_f32_16x16x32_bf16 v[54:57], v[194:197], v[218:221], v[2:5]
	v_mfma_f32_16x16x32_bf16 v[2:5], v[198:201], v[214:217], v[50:53]
	v_mfma_f32_16x16x32_bf16 v[50:53], v[202:205], v[218:221], v[2:5]
	v_mfma_f32_16x16x32_bf16 v[2:5], v[190:193], v[222:225], v[18:21]
	v_mfma_f32_16x16x32_bf16 v[38:41], v[194:197], v[226:229], v[2:5]
	v_mfma_f32_16x16x32_bf16 v[2:5], v[198:201], v[222:225], v[22:25]
	v_mfma_f32_16x16x32_bf16 v[34:37], v[202:205], v[226:229], v[2:5]
	s_setprio 0
	s_barrier
	s_add_i32 s39, s39, 2
	s_add_u32 s6, s6, 0x100
	s_addc_u32 s7, s7, 0
	s_add_u32 s31, s31, 0x100
	s_addc_u32 s35, s35, 0
	s_cmp_gt_u32 s39, 13
	s_cbranch_scc0 .LBB0_1325
	s_and_b64 vcc, exec, s[28:29]
	s_cbranch_vccz .LBB0_1328
	s_barrier

.LBB0_1441:
	s_add_u32 s30, s6, 0x100
	s_addc_u32 s31, s7, 0
	s_add_i32 s70, 0, 0x10000
	s_cmp_eq_u32 s68, 40
	s_cselect_b32 s41, s27, s31
	s_cselect_b32 s40, s26, s30
	s_cselect_b32 s39, s29, s67
	s_cselect_b32 s38, s28, s66
	s_add_i32 s71, 0, 0x14000
	v_add_u32_e32 v78, s70, v203
	v_add_u32_e32 v158, s71, v203
	ds_read_b128 v[66:69], v78
	ds_read_b128 v[70:73], v78 offset:1024
	ds_read_b128 v[74:77], v78 offset:2048
	ds_read_b128 v[78:81], v78 offset:3072
	ds_read_b128 v[146:149], v158
	ds_read_b128 v[150:153], v158 offset:1024
	ds_read_b128 v[154:157], v158 offset:2048
	ds_read_b128 v[158:161], v158 offset:3072
	v_lshl_add_u64 v[200:201], s[6:7], 0, v[172:173]
	s_add_i32 m0, s33, 0xc000
	ds_read_b128 v[162:165], v205
	ds_read_b128 v[176:179], v205 offset:1024
	ds_read_b128 v[180:183], v205 offset:2048
	ds_read_b128 v[184:187], v205 offset:3072
	ds_read_b128 v[188:191], v205 offset:4096
	ds_read_b128 v[192:195], v205 offset:5120
	ds_read_b128 v[196:199], v205 offset:6144
	ds_read_b128 v[206:209], v205 offset:7168
	global_load_lds_dwordx4 v[200:201], off
	v_lshl_add_u64 v[200:201], s[6:7], 0, v[174:175]
	s_add_i32 m0, s33, 0xe000
	s_nop 0
	global_load_lds_dwordx4 v[200:201], off
	s_waitcnt vmcnt(8)
	s_waitcnt lgkmcnt(0)
	s_barrier
	s_setprio 1
	v_mfma_f32_16x16x32_bf16 v[142:145], v[66:69], v[162:165], v[142:145]
	v_mfma_f32_16x16x32_bf16 v[138:141], v[74:77], v[162:165], v[138:141]
	v_mfma_f32_16x16x32_bf16 v[126:129], v[66:69], v[180:183], v[126:129]
	v_mfma_f32_16x16x32_bf16 v[122:125], v[74:77], v[180:183], v[122:125]
	v_mfma_f32_16x16x32_bf16 v[110:113], v[66:69], v[188:191], v[110:113]
	v_mfma_f32_16x16x32_bf16 v[106:109], v[74:77], v[188:191], v[106:109]
	v_mfma_f32_16x16x32_bf16 v[94:97], v[66:69], v[196:199], v[94:97]
	v_mfma_f32_16x16x32_bf16 v[90:93], v[74:77], v[196:199], v[90:93]
	v_mfma_f32_16x16x32_bf16 v[142:145], v[70:73], v[176:179], v[142:145]
	v_mfma_f32_16x16x32_bf16 v[138:141], v[78:81], v[176:179], v[138:141]
	v_mfma_f32_16x16x32_bf16 v[126:129], v[70:73], v[184:187], v[126:129]
	v_mfma_f32_16x16x32_bf16 v[122:125], v[78:81], v[184:187], v[122:125]
	v_mfma_f32_16x16x32_bf16 v[110:113], v[70:73], v[192:195], v[110:113]
	v_mfma_f32_16x16x32_bf16 v[106:109], v[78:81], v[192:195], v[106:109]
	v_mfma_f32_16x16x32_bf16 v[94:97], v[70:73], v[206:209], v[94:97]
	v_mfma_f32_16x16x32_bf16 v[90:93], v[78:81], v[206:209], v[90:93]
	v_mfma_f32_16x16x32_bf16 v[134:137], v[146:149], v[162:165], v[134:137]
	v_mfma_f32_16x16x32_bf16 v[130:133], v[154:157], v[162:165], v[130:133]
	v_mfma_f32_16x16x32_bf16 v[118:121], v[146:149], v[180:183], v[118:121]
	v_mfma_f32_16x16x32_bf16 v[114:117], v[154:157], v[180:183], v[114:117]
	v_mfma_f32_16x16x32_bf16 v[102:105], v[146:149], v[188:191], v[102:105]
	v_mfma_f32_16x16x32_bf16 v[98:101], v[154:157], v[188:191], v[98:101]
	v_mfma_f32_16x16x32_bf16 v[86:89], v[146:149], v[196:199], v[86:89]
	v_mfma_f32_16x16x32_bf16 v[82:85], v[154:157], v[196:199], v[82:85]
	v_mfma_f32_16x16x32_bf16 v[134:137], v[150:153], v[176:179], v[134:137]
	v_mfma_f32_16x16x32_bf16 v[130:133], v[158:161], v[176:179], v[130:133]
	v_mfma_f32_16x16x32_bf16 v[118:121], v[150:153], v[184:187], v[118:121]
	v_mfma_f32_16x16x32_bf16 v[114:117], v[158:161], v[184:187], v[114:117]
	v_mfma_f32_16x16x32_bf16 v[102:105], v[150:153], v[192:195], v[102:105]
	v_mfma_f32_16x16x32_bf16 v[98:101], v[158:161], v[192:195], v[98:101]
	v_mfma_f32_16x16x32_bf16 v[86:89], v[150:153], v[206:209], v[86:89]
	v_mfma_f32_16x16x32_bf16 v[82:85], v[158:161], v[206:209], v[82:85]
	s_setprio 0
	s_barrier
	s_add_i32 s6, s70, s45
	v_lshl_add_u64 v[200:201], s[38:39], 0, v[0:1]
	s_mov_b32 m0, s6
	ds_read_b128 v[162:165], v205 offset:16384
	ds_read_b128 v[176:179], v205 offset:17408
	ds_read_b128 v[180:183], v205 offset:18432
	ds_read_b128 v[184:187], v205 offset:19456
	ds_read_b128 v[188:191], v205 offset:20480
	ds_read_b128 v[192:195], v205 offset:21504
	ds_read_b128 v[196:199], v205 offset:22528
	ds_read_b128 v[206:209], v205 offset:23552
	global_load_lds_dwordx4 v[200:201], off
	s_add_i32 m0, s6, 0x2000
	s_add_u32 s6, s38, 0xb0000
	v_lshl_add_u64 v[210:211], s[38:39], 0, v[170:171]
	s_addc_u32 s7, s39, 0
	s_add_i32 s70, s71, s45
	global_load_lds_dwordx4 v[210:211], off
	v_lshl_add_u64 v[212:213], s[6:7], 0, v[0:1]
	s_mov_b32 m0, s70
	v_lshl_add_u64 v[214:215], s[40:41], 0, v[168:169]
	global_load_lds_dwordx4 v[212:213], off
	v_lshl_add_u64 v[212:213], s[6:7], 0, v[170:171]
	s_add_i32 m0, s70, 0x2000
	s_nop 0
	global_load_lds_dwordx4 v[212:213], off
	v_lshl_add_u64 v[212:213], s[40:41], 0, v[166:167]
	s_mov_b32 m0, s33
	s_nop 0
	global_load_lds_dwordx4 v[212:213], off
	s_mov_b32 m0, s34
	s_nop 0
	global_load_lds_dwordx4 v[214:215], off
	s_waitcnt vmcnt(8)
	s_waitcnt lgkmcnt(0)
	s_barrier
	s_setprio 1
	v_mfma_f32_16x16x32_bf16 v[62:65], v[66:69], v[162:165], v[62:65]
	v_mfma_f32_16x16x32_bf16 v[58:61], v[74:77], v[162:165], v[58:61]
	v_mfma_f32_16x16x32_bf16 v[46:49], v[66:69], v[180:183], v[46:49]
	v_mfma_f32_16x16x32_bf16 v[42:45], v[74:77], v[180:183], v[42:45]
	v_mfma_f32_16x16x32_bf16 v[30:33], v[66:69], v[188:191], v[30:33]
	v_mfma_f32_16x16x32_bf16 v[26:29], v[74:77], v[188:191], v[26:29]
	v_mfma_f32_16x16x32_bf16 v[14:17], v[66:69], v[196:199], v[14:17]
	v_mfma_f32_16x16x32_bf16 v[10:13], v[74:77], v[196:199], v[10:13]
	v_mfma_f32_16x16x32_bf16 v[62:65], v[70:73], v[176:179], v[62:65]
	v_mfma_f32_16x16x32_bf16 v[58:61], v[78:81], v[176:179], v[58:61]
	v_mfma_f32_16x16x32_bf16 v[46:49], v[70:73], v[184:187], v[46:49]
	v_mfma_f32_16x16x32_bf16 v[42:45], v[78:81], v[184:187], v[42:45]
	v_mfma_f32_16x16x32_bf16 v[30:33], v[70:73], v[192:195], v[30:33]
	v_mfma_f32_16x16x32_bf16 v[26:29], v[78:81], v[192:195], v[26:29]
	v_mfma_f32_16x16x32_bf16 v[14:17], v[70:73], v[206:209], v[14:17]
	v_mfma_f32_16x16x32_bf16 v[10:13], v[78:81], v[206:209], v[10:13]
	v_mfma_f32_16x16x32_bf16 v[54:57], v[146:149], v[162:165], v[54:57]
	v_mfma_f32_16x16x32_bf16 v[50:53], v[154:157], v[162:165], v[50:53]
	v_mfma_f32_16x16x32_bf16 v[38:41], v[146:149], v[180:183], v[38:41]
	v_mfma_f32_16x16x32_bf16 v[34:37], v[154:157], v[180:183], v[34:37]
	v_mfma_f32_16x16x32_bf16 v[22:25], v[146:149], v[188:191], v[22:25]
	v_mfma_f32_16x16x32_bf16 v[18:21], v[154:157], v[188:191], v[18:21]
	v_mfma_f32_16x16x32_bf16 v[6:9], v[146:149], v[196:199], v[6:9]
	v_mfma_f32_16x16x32_bf16 v[2:5], v[154:157], v[196:199], v[2:5]
	v_mfma_f32_16x16x32_bf16 v[54:57], v[150:153], v[176:179], v[54:57]
	v_mfma_f32_16x16x32_bf16 v[50:53], v[158:161], v[176:179], v[50:53]
	v_mfma_f32_16x16x32_bf16 v[38:41], v[150:153], v[184:187], v[38:41]
	v_mfma_f32_16x16x32_bf16 v[34:37], v[158:161], v[184:187], v[34:37]
	v_mfma_f32_16x16x32_bf16 v[22:25], v[150:153], v[192:195], v[22:25]
	v_mfma_f32_16x16x32_bf16 v[18:21], v[158:161], v[192:195], v[18:21]
	v_mfma_f32_16x16x32_bf16 v[6:9], v[150:153], v[206:209], v[6:9]
	v_mfma_f32_16x16x32_bf16 v[2:5], v[158:161], v[206:209], v[2:5]
	s_setprio 0
	s_barrier
	s_add_i32 s70, 0, 0x18000
	s_add_i32 s71, 0, 0x1c000
	v_add_u32_e32 v78, s70, v203
	v_add_u32_e32 v158, s71, v203
	ds_read_b128 v[66:69], v78
	ds_read_b128 v[70:73], v78 offset:1024
	ds_read_b128 v[74:77], v78 offset:2048
	ds_read_b128 v[78:81], v78 offset:3072
	ds_read_b128 v[146:149], v158
	ds_read_b128 v[150:153], v158 offset:1024
	ds_read_b128 v[154:157], v158 offset:2048
	ds_read_b128 v[158:161], v158 offset:3072
	s_add_u32 s6, s40, 0xb0000
	s_addc_u32 s7, s41, 0
	s_mov_b32 m0, s35
	v_lshl_add_u64 v[216:217], s[6:7], 0, v[166:167]
	ds_read_b128 v[162:165], v205 offset:32768
	ds_read_b128 v[176:179], v205 offset:33792
	ds_read_b128 v[180:183], v205 offset:34816
	ds_read_b128 v[184:187], v205 offset:35840
	ds_read_b128 v[188:191], v205 offset:36864
	ds_read_b128 v[192:195], v205 offset:37888
	ds_read_b128 v[196:199], v205 offset:38912
	ds_read_b128 v[206:209], v205 offset:39936
	global_load_lds_dwordx4 v[216:217], off
	v_lshl_add_u64 v[216:217], s[6:7], 0, v[168:169]
	s_mov_b32 m0, s46
	s_nop 0
	global_load_lds_dwordx4 v[216:217], off
	s_waitcnt vmcnt(8)
	s_waitcnt lgkmcnt(0)
	s_barrier
	s_setprio 1
	v_mfma_f32_16x16x32_bf16 v[142:145], v[66:69], v[162:165], v[142:145]
	v_mfma_f32_16x16x32_bf16 v[138:141], v[74:77], v[162:165], v[138:141]
	v_mfma_f32_16x16x32_bf16 v[126:129], v[66:69], v[180:183], v[126:129]
	v_mfma_f32_16x16x32_bf16 v[122:125], v[74:77], v[180:183], v[122:125]
	v_mfma_f32_16x16x32_bf16 v[110:113], v[66:69], v[188:191], v[110:113]
	v_mfma_f32_16x16x32_bf16 v[106:109], v[74:77], v[188:191], v[106:109]
	v_mfma_f32_16x16x32_bf16 v[94:97], v[66:69], v[196:199], v[94:97]
	v_mfma_f32_16x16x32_bf16 v[90:93], v[74:77], v[196:199], v[90:93]
	v_mfma_f32_16x16x32_bf16 v[142:145], v[70:73], v[176:179], v[142:145]
	v_mfma_f32_16x16x32_bf16 v[138:141], v[78:81], v[176:179], v[138:141]
	v_mfma_f32_16x16x32_bf16 v[126:129], v[70:73], v[184:187], v[126:129]
	v_mfma_f32_16x16x32_bf16 v[122:125], v[78:81], v[184:187], v[122:125]
	v_mfma_f32_16x16x32_bf16 v[110:113], v[70:73], v[192:195], v[110:113]
	v_mfma_f32_16x16x32_bf16 v[106:109], v[78:81], v[192:195], v[106:109]
	v_mfma_f32_16x16x32_bf16 v[94:97], v[70:73], v[206:209], v[94:97]
	v_mfma_f32_16x16x32_bf16 v[90:93], v[78:81], v[206:209], v[90:93]
	v_mfma_f32_16x16x32_bf16 v[134:137], v[146:149], v[162:165], v[134:137]
	v_mfma_f32_16x16x32_bf16 v[130:133], v[154:157], v[162:165], v[130:133]
	v_mfma_f32_16x16x32_bf16 v[118:121], v[146:149], v[180:183], v[118:121]
	v_mfma_f32_16x16x32_bf16 v[114:117], v[154:157], v[180:183], v[114:117]
	v_mfma_f32_16x16x32_bf16 v[102:105], v[146:149], v[188:191], v[102:105]
	v_mfma_f32_16x16x32_bf16 v[98:101], v[154:157], v[188:191], v[98:101]
	v_mfma_f32_16x16x32_bf16 v[86:89], v[146:149], v[196:199], v[86:89]
	v_mfma_f32_16x16x32_bf16 v[82:85], v[154:157], v[196:199], v[82:85]
	v_mfma_f32_16x16x32_bf16 v[134:137], v[150:153], v[176:179], v[134:137]
	v_mfma_f32_16x16x32_bf16 v[130:133], v[158:161], v[176:179], v[130:133]
	v_mfma_f32_16x16x32_bf16 v[118:121], v[150:153], v[184:187], v[118:121]
	v_mfma_f32_16x16x32_bf16 v[114:117], v[158:161], v[184:187], v[114:117]
	v_mfma_f32_16x16x32_bf16 v[102:105], v[150:153], v[192:195], v[102:105]
	v_mfma_f32_16x16x32_bf16 v[98:101], v[158:161], v[192:195], v[98:101]
	v_mfma_f32_16x16x32_bf16 v[86:89], v[150:153], v[206:209], v[86:89]
	v_mfma_f32_16x16x32_bf16 v[82:85], v[158:161], v[206:209], v[82:85]
	s_setprio 0
	s_barrier
	s_add_i32 s6, s70, s45
	v_lshl_add_u64 v[200:201], v[200:201], 0, s[80:81]
	s_mov_b32 m0, s6
	ds_read_b128 v[162:165], v205 offset:49152
	ds_read_b128 v[176:179], v205 offset:50176
	ds_read_b128 v[180:183], v205 offset:51200
	ds_read_b128 v[184:187], v205 offset:52224
	ds_read_b128 v[188:191], v205 offset:53248
	ds_read_b128 v[192:195], v205 offset:54272
	ds_read_b128 v[196:199], v205 offset:55296
	ds_read_b128 v[206:209], v205 offset:56320
	global_load_lds_dwordx4 v[200:201], off
	s_add_i32 m0, s6, 0x2000
	s_add_u32 s6, s38, 0xb0080
	v_lshl_add_u64 v[200:201], v[210:211], 0, s[80:81]
	s_addc_u32 s7, s39, 0
	s_add_i32 s38, s71, s45
	global_load_lds_dwordx4 v[200:201], off
	v_lshl_add_u64 v[200:201], s[6:7], 0, v[0:1]
	s_mov_b32 m0, s38
	s_nop 0
	global_load_lds_dwordx4 v[200:201], off
	v_lshl_add_u64 v[200:201], s[6:7], 0, v[170:171]
	s_add_i32 m0, s38, 0x2000
	s_nop 0
	global_load_lds_dwordx4 v[200:201], off
	v_lshl_add_u64 v[200:201], v[212:213], 0, s[80:81]
	s_mov_b32 m0, s59
	s_nop 0
	global_load_lds_dwordx4 v[200:201], off
	v_lshl_add_u64 v[200:201], v[214:215], 0, s[80:81]
	s_mov_b32 m0, s61
	s_nop 0
	global_load_lds_dwordx4 v[200:201], off
	s_waitcnt vmcnt(8)
	s_waitcnt lgkmcnt(0)
	s_barrier
	s_setprio 1
	v_mfma_f32_16x16x32_bf16 v[62:65], v[66:69], v[162:165], v[62:65]
	v_mfma_f32_16x16x32_bf16 v[58:61], v[74:77], v[162:165], v[58:61]
	v_mfma_f32_16x16x32_bf16 v[46:49], v[66:69], v[180:183], v[46:49]
	v_mfma_f32_16x16x32_bf16 v[42:45], v[74:77], v[180:183], v[42:45]
	v_mfma_f32_16x16x32_bf16 v[30:33], v[66:69], v[188:191], v[30:33]
	v_mfma_f32_16x16x32_bf16 v[26:29], v[74:77], v[188:191], v[26:29]
	v_mfma_f32_16x16x32_bf16 v[14:17], v[66:69], v[196:199], v[14:17]
	v_mfma_f32_16x16x32_bf16 v[10:13], v[74:77], v[196:199], v[10:13]
	v_mfma_f32_16x16x32_bf16 v[62:65], v[70:73], v[176:179], v[62:65]
	v_mfma_f32_16x16x32_bf16 v[58:61], v[78:81], v[176:179], v[58:61]
	v_mfma_f32_16x16x32_bf16 v[46:49], v[70:73], v[184:187], v[46:49]
	v_mfma_f32_16x16x32_bf16 v[42:45], v[78:81], v[184:187], v[42:45]
	v_mfma_f32_16x16x32_bf16 v[30:33], v[70:73], v[192:195], v[30:33]
	v_mfma_f32_16x16x32_bf16 v[26:29], v[78:81], v[192:195], v[26:29]
	v_mfma_f32_16x16x32_bf16 v[14:17], v[70:73], v[206:209], v[14:17]
	v_mfma_f32_16x16x32_bf16 v[10:13], v[78:81], v[206:209], v[10:13]
	v_mfma_f32_16x16x32_bf16 v[54:57], v[146:149], v[162:165], v[54:57]
	v_mfma_f32_16x16x32_bf16 v[50:53], v[154:157], v[162:165], v[50:53]
	v_mfma_f32_16x16x32_bf16 v[38:41], v[146:149], v[180:183], v[38:41]
	v_mfma_f32_16x16x32_bf16 v[34:37], v[154:157], v[180:183], v[34:37]
	v_mfma_f32_16x16x32_bf16 v[22:25], v[146:149], v[188:191], v[22:25]
	v_mfma_f32_16x16x32_bf16 v[18:21], v[154:157], v[188:191], v[18:21]
	v_mfma_f32_16x16x32_bf16 v[6:9], v[146:149], v[196:199], v[6:9]
	v_mfma_f32_16x16x32_bf16 v[2:5], v[154:157], v[196:199], v[2:5]
	v_mfma_f32_16x16x32_bf16 v[54:57], v[150:153], v[176:179], v[54:57]
	v_mfma_f32_16x16x32_bf16 v[50:53], v[158:161], v[176:179], v[50:53]
	v_mfma_f32_16x16x32_bf16 v[38:41], v[150:153], v[184:187], v[38:41]
	v_mfma_f32_16x16x32_bf16 v[34:37], v[158:161], v[184:187], v[34:37]
	v_mfma_f32_16x16x32_bf16 v[22:25], v[150:153], v[192:195], v[22:25]
	v_mfma_f32_16x16x32_bf16 v[18:21], v[158:161], v[192:195], v[18:21]
	v_mfma_f32_16x16x32_bf16 v[6:9], v[150:153], v[206:209], v[6:9]
	v_mfma_f32_16x16x32_bf16 v[2:5], v[158:161], v[206:209], v[2:5]
	s_setprio 0
	s_barrier
	s_add_i32 s68, s68, 2
	s_add_u32 s66, s66, 0x100
	s_addc_u32 s67, s67, 0
	s_cmp_gt_u32 s68, 41
	s_mov_b64 s[6:7], s[30:31]
	s_cbranch_scc0 .LBB0_1441
	s_and_b64 vcc, exec, s[24:25]
	s_cbranch_vccz .LBB0_1444
	s_barrier
